# attnA: S MFMAs write per-tile register set directly with (cb-mrun) folded into the C operand; removes 32 offset adds per step
# speedup vs baseline: 1.0115x; 1.0064x over previous
; #define FLAS __attribute__((address_space(3)))
; __device__ __forceinline__ void attn_unit_a(FLAS unsigned char* lds, const Unit u) {
;     ...
;     const f32x16 z16 = {0.f,0.f,0.f,0.f,0.f,0.f,0.f,0.f,0.f,0.f,0.f,0.f,0.f,0.f,0.f,0.f};
;     f32x16 o[NDB];
; #pragma unroll
;     for (int i = 0; i < NDB; ++i) o[i] = z16;
;     float mrun = 0.f, lsum = 0.f, fpend = 1.f; bool first = true, pend = false;
;     ...
;     f32x16 pa0, pa1, pb0, pb1; float cbC = 0.f;
;     { bool zi; FA_BIAS(0, pa0, pa1, cbC, zi); if (zi) { pa0 = z16; pa1 = z16; }
;       const FLAS unsigned char* kb = lds + LA_K;
; #pragma unroll
;       for (int d0 = 0; d0 < 4; ++d0) { const int ko = (2 * d0 + hi) * 1024 + ((r32 ^ (2 * d0 + hi)) * 16); const bf16x8 a0 = *(const FLAS bf16x8*)(kb + ko), a1 = *(const FLAS bf16x8*)(kb + ko + 512);
;           pa0 = __builtin_amdgcn_mfma_f32_32x32x16_bf16(a0, qr[d0], pa0, 0, 0, 0); pa1 = __builtin_amdgcn_mfma_f32_32x32x16_bf16(a1, qr[d0], pa1, 0, 0, 0); } }
;     u32x4 pwa[4] = {{0u,0u,0u,0u},{0u,0u,0u,0u},{0u,0u,0u,0u},{0u,0u,0u,0u}}, pwb[4] = {{0u,0u,0u,0u},{0u,0u,0u,0u},{0u,0u,0u,0u},{0u,0u,0u,0u}};
.LBB0_432:
	v_xor_b32_e32 v1, v243, v5
	v_lshlrev_b32_e32 v1, 4, v1
	v_lshl_add_u32 v4, v243, 10, 0
	v_add_u32_e32 v247, v4, v1
	ds_read_b128 v[6:9], v247
	ds_read_b128 v[10:13], v247 offset:512
	v_or_b32_e32 v1, 2, v243
	v_bitop3_b32 v4, v243, v5, 2 bitop3:0x36
	v_lshlrev_b32_e32 v4, 4, v4
	v_lshl_add_u32 v1, v1, 10, 0
	v_add_u32_e32 v248, v1, v4
	s_waitcnt lgkmcnt(1)
	v_mfma_f32_32x32x16_bf16 v[128:143], v[6:9], v[160:163], v[128:143]
	ds_read_b128 v[6:9], v248
	v_or_b32_e32 v1, 4, v243
	v_bitop3_b32 v4, v243, v5, 4 bitop3:0x36
	v_lshlrev_b32_e32 v4, 4, v4
	v_lshl_add_u32 v1, v1, 10, 0
	v_add_u32_e32 v249, v1, v4
	s_lshr_b32 s0, s43, 8
	s_waitcnt lgkmcnt(1)
	v_mfma_f32_32x32x16_bf16 v[144:159], v[10:13], v[160:163], v[144:159]
	ds_read_b128 v[10:13], v248 offset:512
	s_lshl_b32 s15, s41, 1
	s_and_b32 s18, s40, 15
	s_and_b32 s0, s0, 1
	s_lshl_b32 s26, s42, 7
	s_bfe_u32 s1, s41, 0x2000d
	s_and_b32 s15, s15, 0xc000
	s_waitcnt lgkmcnt(1)
	v_mfma_f32_32x32x16_bf16 v[128:143], v[6:9], v[164:167], v[128:143]
	ds_read_b128 v[6:9], v249
	s_lshl_b32 s18, s18, 8
	s_lshl_b32 s20, s0, 7
	s_add_i32 s0, 0, 0x16000
	v_add_u32_e32 v240, s0, v224
	s_add_u32 s0, s70, s15
	s_mul_i32 s19, s1, 0x1800000
	s_waitcnt lgkmcnt(1)
	v_mfma_f32_32x32x16_bf16 v[144:159], v[10:13], v[164:167], v[144:159]
	ds_read_b128 v[10:13], v249 offset:512
	s_addc_u32 s1, s71, 0
	v_or_b32_e32 v1, 6, v243
	v_bitop3_b32 v4, v243, v5, 6 bitop3:0x36
	s_add_u32 s0, s0, s12
	v_lshlrev_b32_e32 v4, 4, v4
	v_lshl_add_u32 v1, v1, 10, 0
	s_waitcnt lgkmcnt(1)
	v_mfma_f32_32x32x16_bf16 v[128:143], v[6:9], v[168:171], v[128:143]
	s_addc_u32 s1, s1, 0
	v_add_u32_e32 v250, v1, v4
	v_lshl_add_u64 v[228:229], s[0:1], 0, v[2:3]
	s_lshl_b32 s0, s5, 8
	ds_read_b128 v[6:9], v250
	ds_read_b128 v[14:17], v250 offset:512
	s_and_b32 s0, s0, 0xfffff000
	s_or_b32 s0, s0, s18
	s_waitcnt lgkmcnt(2)
	v_mfma_f32_32x32x16_bf16 v[144:159], v[10:13], v[168:171], v[144:159]
	s_add_i32 s0, s0, s14
	s_sub_i32 s48, 64, s0
	v_add_lshl_u32 v1, s0, v5, 2
	s_add_u32 s0, s70, s20
	s_addc_u32 s1, s71, 0
	s_add_u32 s0, s0, s4
	s_addc_u32 s1, s1, 0
	s_waitcnt lgkmcnt(1)
	v_mfma_f32_32x32x16_bf16 v[128:143], v[6:9], v[172:175], v[128:143]
	s_add_u32 s0, s0, s19
	s_addc_u32 s1, s1, 0
	v_sub_u32_e32 v1, v224, v1
	v_mov_b64_e32 v[2:3], s[0:1]
	v_mul_u32_u24_e32 v246, 0x90, v5
	v_add_u32_e32 v210, 0, v1
	v_mad_i64_i32 v[230:231], s[0:1], v0, s65, v[2:3]
	s_waitcnt lgkmcnt(0)
	v_mfma_f32_32x32x16_bf16 v[144:159], v[14:17], v[172:175], v[144:159]
	v_mov_b32_e32 v14, v209
	v_mov_b32_e32 v15, v209
	v_mov_b32_e32 v0, v209
	v_mov_b32_e32 v1, v209
	v_mov_b32_e32 v2, v209
	v_mov_b32_e32 v3, v209
	v_mov_b32_e32 v4, v209
	v_mov_b32_e32 v5, v209
	v_mov_b32_e32 v6, v209
	v_mov_b32_e32 v7, v209
	v_mov_b32_e32 v8, v209
	v_mov_b32_e32 v9, v209
	v_mov_b32_e32 v10, v209
	v_mov_b32_e32 v11, v209
	v_mov_b32_e32 v12, v209
	v_mov_b32_e32 v13, v209
	v_mov_b32_e32 v188, 0
	v_mov_b64_e32 v[30:31], v[14:15]
	v_mov_b64_e32 v[46:47], v[14:15]
	v_mov_b64_e32 v[62:63], v[14:15]
	v_ashrrev_i32_e32 v223, 31, v222
	v_add3_u32 v251, 0, v246, v224
	s_mov_b32 s49, 0
	s_mov_b64 s[24:25], -1
	v_mov_b32_e32 v211, 0
	v_mov_b32_e32 v226, 1.0
	v_mov_b64_e32 v[28:29], v[12:13]
	v_mov_b64_e32 v[26:27], v[10:11]
	v_mov_b64_e32 v[24:25], v[8:9]
	v_mov_b64_e32 v[22:23], v[6:7]
	v_mov_b64_e32 v[20:21], v[4:5]
	v_mov_b64_e32 v[18:19], v[2:3]
	v_mov_b64_e32 v[16:17], v[0:1]
	v_mov_b64_e32 v[44:45], v[12:13]
	v_mov_b64_e32 v[42:43], v[10:11]
	v_mov_b64_e32 v[40:41], v[8:9]
	v_mov_b64_e32 v[38:39], v[6:7]
	v_mov_b64_e32 v[36:37], v[4:5]
	v_mov_b64_e32 v[34:35], v[2:3]
	v_mov_b64_e32 v[32:33], v[0:1]
	v_mov_b64_e32 v[60:61], v[12:13]
	v_mov_b64_e32 v[58:59], v[10:11]
	v_mov_b64_e32 v[56:57], v[8:9]
	v_mov_b64_e32 v[54:55], v[6:7]
	v_mov_b64_e32 v[52:53], v[4:5]
	v_mov_b64_e32 v[50:51], v[2:3]
	v_mov_b64_e32 v[48:49], v[0:1]
	s_mov_b32 s19, 0
	v_mov_b32_e32 v212, 0
	v_mov_b32_e32 v189, v188
	v_mov_b32_e32 v190, v188
	v_mov_b32_e32 v191, v188
	v_mov_b32_e32 v192, v188
	v_mov_b32_e32 v193, v188
	v_mov_b32_e32 v194, v188
	v_mov_b32_e32 v195, v188
	v_mov_b32_e32 v196, v188
	v_mov_b32_e32 v197, v188
	v_mov_b32_e32 v198, v188
	v_mov_b32_e32 v199, v188
	v_mov_b32_e32 v104, v188
	v_mov_b32_e32 v105, v188
	v_mov_b32_e32 v106, v188
	v_mov_b32_e32 v107, v188
	s_waitcnt lgkmcnt(0)
	v_readlane_b32 s100, v254, 47
	v_mov_b32_e32 v92, s13
	s_nop 3
	v_mov_b32_e32 v93, s100
	ds_read_b32 v92, v92
	ds_read_b32 v93, v93
	v_sub_f32_e32 v94, v204, v211
	v_add_f32_e32 v96, v128, v94
	v_add_f32_e32 v112, v144, v94
	v_add_f32_e32 v97, v129, v94
	v_add_f32_e32 v113, v145, v94
	v_add_f32_e32 v98, v130, v94
	v_add_f32_e32 v114, v146, v94
	v_add_f32_e32 v99, v131, v94
	v_add_f32_e32 v115, v147, v94
	v_add_f32_e32 v100, v132, v94
	v_add_f32_e32 v116, v148, v94
	v_add_f32_e32 v101, v133, v94
	v_add_f32_e32 v117, v149, v94
	v_add_f32_e32 v102, v134, v94
	v_add_f32_e32 v118, v150, v94
	v_add_f32_e32 v103, v135, v94
	v_add_f32_e32 v119, v151, v94
	v_add_f32_e32 v104, v136, v94
	v_add_f32_e32 v120, v152, v94
	v_add_f32_e32 v105, v137, v94
	v_add_f32_e32 v121, v153, v94
	v_add_f32_e32 v106, v138, v94
	v_add_f32_e32 v122, v154, v94
	v_add_f32_e32 v107, v139, v94
	v_add_f32_e32 v123, v155, v94
	v_add_f32_e32 v108, v140, v94
	v_add_f32_e32 v124, v156, v94
	v_add_f32_e32 v109, v141, v94
	v_add_f32_e32 v125, v157, v94
	v_add_f32_e32 v110, v142, v94
	v_add_f32_e32 v126, v158, v94
	v_add_f32_e32 v111, v143, v94
	v_add_f32_e32 v127, v159, v94
	v_mov_b32_e32 v144, 0x7fc00000
	v_mov_b32_e32 v145, 0x7fc00000
	v_mov_b32_e32 v146, 0x7fc00000
	v_mov_b32_e32 v147, 0x7fc00000
	v_mov_b32_e32 v148, 0x7fc00000
	v_mov_b32_e32 v149, 0x7fc00000
	v_mov_b32_e32 v150, 0x7fc00000
	v_mov_b32_e32 v151, 0x7fc00000
	v_mov_b32_e32 v152, 0x7fc00000
	v_mov_b32_e32 v153, 0x7fc00000
	v_mov_b32_e32 v154, 0x7fc00000
	v_mov_b32_e32 v155, 0x7fc00000
	v_mov_b32_e32 v156, 0x7fc00000
	v_mov_b32_e32 v157, 0x7fc00000
	v_mov_b32_e32 v158, 0x7fc00000
	v_mov_b32_e32 v159, 0x7fc00000
	v_mov_b32_e32 v204, 0
	v_mov_b32_e32 v205, 0
	v_mov_b32_e32 v206, 0
	v_mov_b32_e32 v207, 0
	s_waitcnt lgkmcnt(0)
	v_readfirstlane_b32 s101, v92
	v_readfirstlane_b32 s100, v93
	s_cbranch_execnz .LBB0_435
	s_branch .LBB0_434

; #define FLAS __attribute__((address_space(3)))
; __device__ __forceinline__ void attn_unit_a(FLAS unsigned char* lds, const Unit u) {
;     ...
;         if (i + 2 < NT) { kreg = *(const u32x4*)(ksrc + (size_t)(u.t_lo + i + 2) * 64 * u.ldk);
; #pragma unroll
;             for (int j = 0; j < 2; ++j) vreg[j] = *(const u32x4*)(vsrc + (size_t)j * 64 * MTOK + (u.t_lo + i + 2) * 64); }
;         const int vsp = (i == 0) ? 0 : ((i - 1) & 3);
;         const FLAS unsigned char* vb_ = lds + LA_V + vsp * VBUF + r32 * VPITCH + hi * 16;
;         const FLAS unsigned char* kb = lds + LA_K + ((i + 1) & 1) * KBUF;
;     ...
;         u32x4 vr[3];
; #pragma unroll
;         for (int m = 0; m < 3; ++m) vr[m] = FA_VFRAG(m);
;         const float off = cbC - mrun;
;         FA_SB();
;         float ra, rb, rm;
;         FA_PVM(0); pC0[0] = fadd_s(pC0[0], off); pC1[0] = fadd_s(pC1[0], off); pC0[1] = fadd_s(pC0[1], off); pC1[1] = fadd_s(pC1[1], off); pC0[2] = fadd_s(pC0[2], off); pC1[2] = fadd_s(pC1[2], off); FA_SB();
;         FA_PVM(1); ra = __builtin_fmaxf(__builtin_fmaxf(pC0[0], pC0[1]), pC0[2]); rb = __builtin_fmaxf(__builtin_fmaxf(pC1[0], pC1[1]), pC1[2]); pC0[3] = fadd_s(pC0[3], off); pC1[3] = fadd_s(pC1[3], off); pC0[4] = fadd_s(pC0[4], off); pC1[4] = fadd_s(pC1[4], off); FA_SB();
;         FA_PVM(2); ra = __builtin_fmaxf(__builtin_fmaxf(ra, pC0[3]), pC0[4]); rb = __builtin_fmaxf(__builtin_fmaxf(rb, pC1[3]), pC1[4]); pC0[5] = fadd_s(pC0[5], off); pC1[5] = fadd_s(pC1[5], off); pC0[6] = fadd_s(pC0[6], off); pC1[6] = fadd_s(pC1[6], off); FA_SB();
;         FA_PVM(3); ra = __builtin_fmaxf(__builtin_fmaxf(ra, pC0[5]), pC0[6]); rb = __builtin_fmaxf(__builtin_fmaxf(rb, pC1[5]), pC1[6]); pC0[7] = fadd_s(pC0[7], off); pC1[7] = fadd_s(pC1[7], off); pC0[8] = fadd_s(pC0[8], off); pC1[8] = fadd_s(pC1[8], off); FA_SB();
;         FA_PVM(4); ra = __builtin_fmaxf(__builtin_fmaxf(ra, pC0[7]), pC0[8]); rb = __builtin_fmaxf(__builtin_fmaxf(rb, pC1[7]), pC1[8]); pC0[9] = fadd_s(pC0[9], off); pC1[9] = fadd_s(pC1[9], off); pC0[10] = fadd_s(pC0[10], off); pC1[10] = fadd_s(pC1[10], off); FA_SB();
;         FA_PVM(5); ra = __builtin_fmaxf(__builtin_fmaxf(ra, pC0[9]), pC0[10]); rb = __builtin_fmaxf(__builtin_fmaxf(rb, pC1[9]), pC1[10]); pC0[11] = fadd_s(pC0[11], off); pC1[11] = fadd_s(pC1[11], off); pC0[12] = fadd_s(pC0[12], off); pC1[12] = fadd_s(pC1[12], off); FA_SB();
.LBB0_435:
	s_cmpk_lt_u32 s19, 0x7e
	s_cselect_b64 s[0:1], -1, 0
	s_cmpk_gt_u32 s19, 0x7d
	s_cselect_b64 s[4:5], -1, 0
	s_and_b64 vcc, exec, s[4:5]
	v_lshl_add_u64 v[234:235], v[230:231], 0, v[208:209]
	v_lshl_add_u64 v[232:233], v[228:229], 0, v[208:209]
	s_cbranch_vccnz .LBB0_437
	v_add_co_u32_e32 v128, vcc, 0xd660000, v234
	s_nop 1
	v_addc_co_u32_e32 v129, vcc, 0, v235, vcc
	global_load_dwordx4 v[176:179], v[128:129], off
	v_add_co_u32_e32 v128, vcc, 0x13600000, v232
	s_nop 1
	v_addc_co_u32_e32 v129, vcc, 0, v233, vcc
	v_add_co_u32_e32 v130, vcc, 0x13a00000, v232
	s_nop 1
	v_addc_co_u32_e32 v131, vcc, 0, v233, vcc
	global_load_dwordx4 v[180:183], v[128:129], off offset:256
	global_load_dwordx4 v[184:187], v[130:131], off offset:256
.LBB0_437:
	s_add_i32 s12, s19, -1
	s_xor_b64 s[20:21], s[24:25], -1
	s_and_b32 s18, s12, 3
	s_mulk_i32 s18, 0x4800
	s_cmp_lg_u32 s49, 0
	s_cselect_b32 s12, s18, 0
	v_add_u32_e32 v200, s12, v251
	ds_read_b128 v[128:131], v200 offset:16384
	ds_read_b128 v[132:135], v200 offset:20992
	ds_read_b128 v[136:139], v200 offset:25600
	s_waitcnt lgkmcnt(2)
	v_mfma_f32_32x32x16_bf16 v[48:63], v[128:131], v[204:207], v[48:63]
	ds_read_b128 v[128:131], v200 offset:30208
	v_max3_f32 v92, v96, v97, v98
	v_max3_f32 v93, v112, v113, v114
	s_waitcnt lgkmcnt(2)
	v_mfma_f32_32x32x16_bf16 v[32:47], v[132:135], v[204:207], v[32:47]
	ds_read_b128 v[132:135], v200 offset:16416
	v_max3_f32 v92, v92, v99, v100
	v_max3_f32 v93, v93, v115, v116
	s_waitcnt lgkmcnt(2)
	v_mfma_f32_32x32x16_bf16 v[16:31], v[136:139], v[204:207], v[16:31]
	ds_read_b128 v[136:139], v200 offset:21024
	v_max3_f32 v92, v92, v101, v102
	v_max3_f32 v93, v93, v117, v118
	s_waitcnt lgkmcnt(2)
	v_mfma_f32_32x32x16_bf16 v[0:15], v[128:131], v[204:207], v[0:15]
	ds_read_b128 v[128:131], v200 offset:25632
	v_max3_f32 v92, v92, v103, v104
	v_max3_f32 v93, v93, v119, v120
	s_waitcnt lgkmcnt(2)
	v_mfma_f32_32x32x16_bf16 v[48:63], v[132:135], v[196:199], v[48:63]
	ds_read_b128 v[132:135], v200 offset:30240
	v_max3_f32 v92, v92, v105, v106
	v_max3_f32 v93, v93, v121, v122
	s_waitcnt lgkmcnt(2)
	v_mfma_f32_32x32x16_bf16 v[32:47], v[136:139], v[196:199], v[32:47]
	ds_read_b128 v[136:139], v200 offset:16448
	v_max3_f32 v92, v92, v107, v108
	v_max3_f32 v93, v93, v123, v124
	s_waitcnt lgkmcnt(2)
	v_mfma_f32_32x32x16_bf16 v[16:31], v[128:131], v[196:199], v[16:31]
	ds_read_b128 v[128:131], v200 offset:21056
	v_max3_f32 v92, v92, v109, v110
	v_max3_f32 v93, v93, v125, v126
	s_waitcnt lgkmcnt(2)
	v_mfma_f32_32x32x16_bf16 v[0:15], v[132:135], v[196:199], v[0:15]
	ds_read_b128 v[132:135], v200 offset:25664
	v_max3_f32 v92, v92, v93, v111
	v_max_f32_e32 v92, v92, v127
	v_mov_b32_e32 v93, v92
	s_nop 1
	v_permlane32_swap_b32 v92, v93
	s_nop 1
	s_nop 0
	v_max_f32_e32 v92, v92, v93
	s_andn2_b64 vcc, exec, s[20:21]
	s_cbranch_vccnz .LBB0_440
	v_cmp_lt_f32_e32 vcc, s39, v92
	s_cmp_lg_u64 vcc, 0
	s_mov_b32 s12, 0
	s_cselect_b64 s[14:15], -1, 0
	v_mov_b32_e32 v93, v211
	s_andn2_b64 vcc, exec, s[14:15]
	s_cbranch_vccz .LBB0_441

; #define FA_SB() __builtin_amdgcn_sched_barrier(0)
; #define FA_PVM(G) do { o[(G) & 3] = __builtin_amdgcn_mfma_f32_32x32x16_bf16(__builtin_bit_cast(bf16x8, vr[(G) % 3]), __builtin_bit_cast(bf16x8, PWC[(G) >> 2]), o[(G) & 3], 0, 0, 0); if ((G) + 3 < 16) vr[(G) % 3] = FA_VFRAG((G) + 3); } while (0)
; #define FA_EXP2(J, PX, R) do { const float e0_ = __builtin_amdgcn_exp2f(PX[R]), e1_ = __builtin_amdgcn_exp2f(PX[(R) + 1]); ps += e0_; ps += e1_; PWN[(J) >> 2][(J) & 3] = cvtpk(e0_, e1_); } while (0)
; __device__ __forceinline__ void attn_unit_a(FLAS unsigned char* lds, const Unit u) {
;     ...
;         if (first || __any(rm > 8.0f)) {
;             const float dl = __builtin_fmaxf(rm, first ? -1000.0f : 0.0f); const float f = first ? 1.0f : __builtin_amdgcn_exp2f(-dl);
;             mrun = first ? dl : mrun + dl; lsum *= f; fpend = f; pend = !first; first = false;
; #pragma unroll
;             for (int r = 0; r < 16; ++r) { pC0[r] = pC0[r] - dl; pC1[r] = pC1[r] - dl; }
;         }
;         float ps = 0.f;
;         bf16x8 kf[4];
; #pragma unroll
;         for (int g = 8; g < 16; ++g) { FA_PVM(g); FA_EXP2(g - 8, pC0, 2 * (g - 8));
;             if (g == 12) { kf[0] = FA_KF(0, 0); kf[1] = FA_KF(0, 1); kf[2] = FA_KF(1, 0); kf[3] = FA_KF(1, 1); }
;             FA_SB(); }
;         float cbN; bool ziN; const int inx = (i + 1 < NT) ? i + 1 : NT - 1;
;         FA_BIAS(inx, pN0, pN1, cbN, ziN);
;         FA_SB();
;         if (ziN) { pN0 = __builtin_amdgcn_mfma_f32_32x32x16_bf16(kf[0], qr[0], z16, 0, 0, 0); FA_EXP2(8, pC1, 0); FA_SB(); pN1 = __builtin_amdgcn_mfma_f32_32x32x16_bf16(kf[1], qr[0], z16, 0, 0, 0); }
;         else { pN0 = __builtin_amdgcn_mfma_f32_32x32x16_bf16(kf[0], qr[0], pN0, 0, 0, 0); FA_EXP2(8, pC1, 0); FA_SB(); pN1 = __builtin_amdgcn_mfma_f32_32x32x16_bf16(kf[1], qr[0], pN1, 0, 0, 0); }
.LBB0_440:
	v_bfrev_b32_e32 v93, 1
	s_mov_b32 s12, 0xc47a0000
	s_mov_b64 s[14:15], s[24:25]
	s_andn2_b64 vcc, exec, s[14:15]
	s_cbranch_vccnz .LBB0_439
.LBB0_441:
	v_max_f32_e64 v94, s12, s12
	v_max_f32_e32 v92, v92, v92
	v_max_f32_e32 v92, v92, v94
	v_exp_f32_e64 v94, -v92
	v_add_f32_e32 v211, v93, v92
	v_sub_f32_e32 v111, v111, v92
	v_sub_f32_e32 v110, v110, v92
	v_cndmask_b32_e64 v226, v94, 1.0, s[24:25]
	v_mul_f32_e32 v212, v212, v226
	v_sub_f32_e32 v109, v109, v92
	v_sub_f32_e32 v108, v108, v92
	v_sub_f32_e32 v107, v107, v92
	v_sub_f32_e32 v106, v106, v92
	v_sub_f32_e32 v105, v105, v92
	v_sub_f32_e32 v104, v104, v92
	v_sub_f32_e32 v103, v103, v92
	v_sub_f32_e32 v102, v102, v92
	v_sub_f32_e32 v101, v101, v92
	v_sub_f32_e32 v100, v100, v92
	v_sub_f32_e32 v99, v99, v92
	v_sub_f32_e32 v98, v98, v92
	v_sub_f32_e32 v97, v97, v92
	v_sub_f32_e32 v96, v96, v92
	v_sub_f32_e32 v127, v127, v92
	v_sub_f32_e32 v126, v126, v92
	v_sub_f32_e32 v125, v125, v92
	v_sub_f32_e32 v124, v124, v92
	v_sub_f32_e32 v123, v123, v92
	v_sub_f32_e32 v122, v122, v92
	v_sub_f32_e32 v121, v121, v92
	v_sub_f32_e32 v120, v120, v92
	v_sub_f32_e32 v119, v119, v92
	v_sub_f32_e32 v118, v118, v92
	v_sub_f32_e32 v117, v117, v92
	v_sub_f32_e32 v116, v116, v92
	v_sub_f32_e32 v115, v115, v92
	v_sub_f32_e32 v114, v114, v92
	v_sub_f32_e32 v113, v113, v92
	v_sub_f32_e32 v112, v112, v92
.LBB0_442:
	s_waitcnt lgkmcnt(2)
	v_mfma_f32_32x32x16_bf16 v[48:63], v[136:139], v[192:195], v[48:63]
	ds_read_b128 v[136:139], v200 offset:30272
	v_exp_f32_e32 v96, v96
	v_exp_f32_e32 v97, v97
	s_waitcnt lgkmcnt(2)
	v_mfma_f32_32x32x16_bf16 v[32:47], v[128:131], v[192:195], v[32:47]
	ds_read_b128 v[128:131], v200 offset:16480
	v_exp_f32_e32 v98, v98
	v_exp_f32_e32 v99, v99
	v_add_f32_e32 v212, v96, v212
	v_add_f32_e32 v212, v97, v212
	s_waitcnt lgkmcnt(2)
	v_mfma_f32_32x32x16_bf16 v[16:31], v[132:135], v[192:195], v[16:31]
	ds_read_b128 v[132:135], v200 offset:21088
	v_exp_f32_e32 v100, v100
	v_exp_f32_e32 v101, v101
	v_add_f32_e32 v212, v98, v212
	v_add_f32_e32 v212, v99, v212
	s_waitcnt lgkmcnt(2)
	v_mfma_f32_32x32x16_bf16 v[0:15], v[136:139], v[192:195], v[0:15]
	ds_read_b128 v[136:139], v200 offset:25696
	v_exp_f32_e32 v102, v102
	v_exp_f32_e32 v103, v103
	v_add_f32_e32 v212, v100, v212
	v_add_f32_e32 v212, v101, v212
	s_waitcnt lgkmcnt(2)
	v_mfma_f32_32x32x16_bf16 v[48:63], v[128:131], v[188:191], v[48:63]
	ds_read_b128 v[128:131], v200 offset:30304
	ds_read_b128 v[204:207], v247 offset:8192
	ds_read_b128 v[200:203], v247 offset:8704
	ds_read_b128 v[196:199], v248 offset:8192
	ds_read_b128 v[192:195], v248 offset:8704
	v_exp_f32_e32 v104, v104
	v_exp_f32_e32 v105, v105
	v_add_f32_e32 v212, v102, v212
	v_add_f32_e32 v212, v103, v212
	s_waitcnt lgkmcnt(6)
	v_mfma_f32_32x32x16_bf16 v[32:47], v[132:135], v[188:191], v[32:47]
	v_exp_f32_e32 v106, v106
	v_exp_f32_e32 v107, v107
	v_add_f32_e32 v212, v104, v212
	v_add_f32_e32 v212, v105, v212
	s_waitcnt lgkmcnt(5)
	v_mfma_f32_32x32x16_bf16 v[16:31], v[136:139], v[188:191], v[16:31]
	v_exp_f32_e32 v108, v108
	v_exp_f32_e32 v109, v109
	v_add_f32_e32 v212, v106, v212
	v_add_f32_e32 v212, v107, v212
	s_waitcnt lgkmcnt(4)
	v_mfma_f32_32x32x16_bf16 v[0:15], v[128:131], v[188:191], v[0:15]
	v_exp_f32_e32 v110, v110
	v_exp_f32_e32 v111, v111
	v_add_f32_e32 v212, v108, v212
	v_add_f32_e32 v212, v109, v212
	s_sub_i32 s12, s48, 31
	s_cmpk_lt_i32 s12, 0x22f
	s_cbranch_scc0 .Lz_plus_e
	s_cmpk_gt_i32 s48, 0xfd92
	s_cbranch_scc1 .Lgather_e
	v_sub_f32_e32 v94, s100, v211
	s_branch .Lz_chk_e
.Lz_plus_e:
	v_sub_f32_e32 v94, s101, v211
.Lz_chk_e:
	v_cmp_neq_f32_e32 vcc, v94, v144
	s_cbranch_vccz .Lz_go_e
	v_mov_b32_e32 v144, v94
	v_mov_b32_e32 v145, v94
	v_mov_b32_e32 v146, v94
	v_mov_b32_e32 v147, v94
	v_mov_b32_e32 v148, v94
	v_mov_b32_e32 v149, v94
	v_mov_b32_e32 v150, v94
	v_mov_b32_e32 v151, v94
	v_mov_b32_e32 v152, v94
	v_mov_b32_e32 v153, v94
	v_mov_b32_e32 v154, v94
	v_mov_b32_e32 v155, v94
	v_mov_b32_e32 v156, v94
	v_mov_b32_e32 v157, v94
	v_mov_b32_e32 v158, v94
	v_mov_b32_e32 v159, v94
	s_nop 1
.Lz_go_e:
	s_waitcnt lgkmcnt(0)
	v_mfma_f32_32x32x16_bf16 v[64:79], v[204:207], v[160:163], v[144:159]
	v_exp_f32_e32 v112, v112
	v_exp_f32_e32 v113, v113
	v_add_f32_e32 v212, v110, v212
	v_add_f32_e32 v212, v111, v212
	v_mfma_f32_32x32x16_bf16 v[80:95], v[200:203], v[160:163], v[144:159]
	v_exp_f32_e32 v114, v114
	v_exp_f32_e32 v115, v115
	v_add_f32_e32 v212, v112, v212
	v_add_f32_e32 v212, v113, v212
	s_branch .Lk2_e
; #define FLAS __attribute__((address_space(3)))
; #define FA_SB() __builtin_amdgcn_sched_barrier(0)
; #define FA_EXP2(J, PX, R) do { const float e0_ = __builtin_amdgcn_exp2f(PX[R]), e1_ = __builtin_amdgcn_exp2f(PX[(R) + 1]); ps += e0_; ps += e1_; PWN[(J) >> 2][(J) & 3] = cvtpk(e0_, e1_); } while (0)
; __device__ __forceinline__ void attn_unit_a(FLAS unsigned char* lds, const Unit u) {
;     ...
;         float cbN; bool ziN; const int inx = (i + 1 < NT) ? i + 1 : NT - 1;
;         FA_BIAS(inx, pN0, pN1, cbN, ziN);
;         FA_SB();
;         if (ziN) { pN0 = __builtin_amdgcn_mfma_f32_32x32x16_bf16(kf[0], qr[0], z16, 0, 0, 0); FA_EXP2(8, pC1, 0); FA_SB(); pN1 = __builtin_amdgcn_mfma_f32_32x32x16_bf16(kf[1], qr[0], z16, 0, 0, 0); }
;         else { pN0 = __builtin_amdgcn_mfma_f32_32x32x16_bf16(kf[0], qr[0], pN0, 0, 0, 0); FA_EXP2(8, pC1, 0); FA_SB(); pN1 = __builtin_amdgcn_mfma_f32_32x32x16_bf16(kf[1], qr[0], pN1, 0, 0, 0); }
;         kf[0] = FA_KF(2, 0); kf[1] = FA_KF(2, 1); FA_EXP2(9, pC1, 2); FA_SB();
;         pN0 = __builtin_amdgcn_mfma_f32_32x32x16_bf16(kf[2], qr[1], pN0, 0, 0, 0); FA_EXP2(10, pC1, 4); FA_SB();
;         pN1 = __builtin_amdgcn_mfma_f32_32x32x16_bf16(kf[3], qr[1], pN1, 0, 0, 0); kf[2] = FA_KF(3, 0); kf[3] = FA_KF(3, 1); FA_EXP2(11, pC1, 6); FA_SB();
;         pN0 = __builtin_amdgcn_mfma_f32_32x32x16_bf16(kf[0], qr[2], pN0, 0, 0, 0); FA_EXP2(12, pC1, 8); FA_SB();
;         pN1 = __builtin_amdgcn_mfma_f32_32x32x16_bf16(kf[1], qr[2], pN1, 0, 0, 0); FA_EXP2(13, pC1, 10); FA_SB();
;         pN0 = __builtin_amdgcn_mfma_f32_32x32x16_bf16(kf[2], qr[3], pN0, 0, 0, 0); FA_EXP2(14, pC1, 12); FA_SB();
;         pN1 = __builtin_amdgcn_mfma_f32_32x32x16_bf16(kf[3], qr[3], pN1, 0, 0, 0); FA_EXP2(15, pC1, 14); FA_SB();
;     ...
;         lsum += ps; cbC = cbN;
;         if (i + 2 < NT) { *(FLAS u32x4*)(lds + LA_K + (i & 1) * KBUF + kdst) = kreg;
; #pragma unroll
;             for (int j = 0; j < 2; ++j) { *(FLAS u32x2*)(lds + LA_V + ((i + 2) & 3) * VBUF + vdst + j * 64 * VPITCH) = (u32x2){vreg[j].x, vreg[j].y}; *(FLAS u32x2*)(lds + LA_V + ((i + 2) & 3) * VBUF + vdst + j * 64 * VPITCH + 16) = (u32x2){vreg[j].z, vreg[j].w}; } }
.Lgather_e:
	v_add_u32_e32 v76, s49, v210
	v_add_u32_e32 v64, 0x17600, v76
	v_add_u32_e32 v66, 0x17680, v76
	v_add_u32_e32 v67, 0x17608, v76
	v_add_u32_e32 v68, 0x17688, v76
	ds_read2_b32 v[64:65], v64 offset1:1
	ds_read2_b32 v[80:81], v66 offset1:1
	ds_read2_b32 v[66:67], v67 offset1:1
	ds_read2_b32 v[82:83], v68 offset1:1
	v_add_u32_e32 v68, 0x17620, v76
	v_add_u32_e32 v70, 0x176a0, v76
	v_add_u32_e32 v71, 0x17628, v76
	v_add_u32_e32 v72, 0x176a8, v76
	ds_read2_b32 v[68:69], v68 offset1:1
	ds_read2_b32 v[84:85], v70 offset1:1
	ds_read2_b32 v[70:71], v71 offset1:1
	ds_read2_b32 v[86:87], v72 offset1:1
	v_add_u32_e32 v72, 0x17640, v76
	v_add_u32_e32 v74, 0x176c0, v76
	v_add_u32_e32 v75, 0x17648, v76
	v_add_u32_e32 v77, 0x176c8, v76
	ds_read2_b32 v[72:73], v72 offset1:1
	ds_read2_b32 v[88:89], v74 offset1:1
	ds_read2_b32 v[74:75], v75 offset1:1
	ds_read2_b32 v[90:91], v77 offset1:1
	v_add_u32_e32 v77, 0x17660, v76
	v_add_u32_e32 v78, 0x176e0, v76
	v_add_u32_e32 v79, 0x17668, v76
	v_add_u32_e32 v94, 0x176e8, v76
	ds_read2_b32 v[76:77], v77 offset1:1
	ds_read2_b32 v[92:93], v78 offset1:1
	ds_read2_b32 v[78:79], v79 offset1:1
	ds_read2_b32 v[94:95], v94 offset1:1
	s_waitcnt lgkmcnt(0)
	v_sub_f32_e32 v64, v64, v211
	v_sub_f32_e32 v65, v65, v211
	v_sub_f32_e32 v66, v66, v211
	v_sub_f32_e32 v67, v67, v211
	v_sub_f32_e32 v68, v68, v211
	v_sub_f32_e32 v69, v69, v211
	v_sub_f32_e32 v70, v70, v211
	v_sub_f32_e32 v71, v71, v211
	v_sub_f32_e32 v72, v72, v211
	v_sub_f32_e32 v73, v73, v211
	v_sub_f32_e32 v74, v74, v211
	v_sub_f32_e32 v75, v75, v211
	v_sub_f32_e32 v76, v76, v211
	v_sub_f32_e32 v77, v77, v211
	v_sub_f32_e32 v78, v78, v211
	v_sub_f32_e32 v79, v79, v211
	v_sub_f32_e32 v80, v80, v211
	v_sub_f32_e32 v81, v81, v211
	v_sub_f32_e32 v82, v82, v211
	v_sub_f32_e32 v83, v83, v211
	v_sub_f32_e32 v84, v84, v211
	v_sub_f32_e32 v85, v85, v211
	v_sub_f32_e32 v86, v86, v211
	v_sub_f32_e32 v87, v87, v211
	v_sub_f32_e32 v88, v88, v211
	v_sub_f32_e32 v89, v89, v211
	v_sub_f32_e32 v90, v90, v211
	v_sub_f32_e32 v91, v91, v211
	v_sub_f32_e32 v92, v92, v211
	v_sub_f32_e32 v93, v93, v211
	v_sub_f32_e32 v94, v94, v211
	v_sub_f32_e32 v95, v95, v211
	s_nop 1
	v_mfma_f32_32x32x16_bf16 v[64:79], v[204:207], v[160:163], v[64:79]
	v_exp_f32_e32 v112, v112
	v_exp_f32_e32 v113, v113
	v_add_f32_e32 v212, v110, v212
	v_add_f32_e32 v212, v111, v212
	v_mfma_f32_32x32x16_bf16 v[80:95], v[200:203], v[160:163], v[80:95]
	v_exp_f32_e32 v114, v114
	v_exp_f32_e32 v115, v115
	v_add_f32_e32 v212, v112, v212
	v_add_f32_e32 v212, v113, v212
.Lk2_e:
	ds_read_b128 v[128:131], v249 offset:8192
	ds_read_b128 v[132:135], v249 offset:8704
	s_add_i32 s34, s19, 2
	v_mfma_f32_32x32x16_bf16 v[64:79], v[196:199], v[164:167], v[64:79]
	v_exp_f32_e32 v116, v116
	v_exp_f32_e32 v117, v117
	v_add_f32_e32 v212, v114, v212
	v_add_f32_e32 v212, v115, v212
	v_mfma_f32_32x32x16_bf16 v[80:95], v[192:195], v[164:167], v[80:95]
	ds_read_b128 v[136:139], v250 offset:8192
	ds_read_b128 v[140:143], v250 offset:8704
	v_exp_f32_e32 v118, v118
	v_exp_f32_e32 v119, v119
	v_add_f32_e32 v212, v116, v212
	v_add_f32_e32 v212, v117, v212
	s_waitcnt lgkmcnt(3)
	v_mfma_f32_32x32x16_bf16 v[64:79], v[128:131], v[168:171], v[64:79]
	v_exp_f32_e32 v120, v120
	v_exp_f32_e32 v121, v121
	v_add_f32_e32 v212, v118, v212
	v_add_f32_e32 v212, v119, v212
	s_waitcnt lgkmcnt(2)
	v_mfma_f32_32x32x16_bf16 v[80:95], v[132:135], v[168:171], v[80:95]
	v_exp_f32_e32 v122, v122
	v_exp_f32_e32 v123, v123
	v_add_f32_e32 v212, v120, v212
	v_add_f32_e32 v212, v121, v212
	s_waitcnt lgkmcnt(1)
	v_mfma_f32_32x32x16_bf16 v[64:79], v[136:139], v[172:175], v[64:79]
	v_exp_f32_e32 v124, v124
	v_exp_f32_e32 v125, v125
	v_add_f32_e32 v212, v122, v212
	v_add_f32_e32 v212, v123, v212
	s_waitcnt lgkmcnt(0)
	v_mfma_f32_32x32x16_bf16 v[80:95], v[140:143], v[172:175], v[80:95]
	v_exp_f32_e32 v126, v126
	v_exp_f32_e32 v127, v127
	v_add_f32_e32 v212, v124, v212
	v_add_f32_e32 v212, v125, v212
	v_add_f32_e32 v212, v126, v212
	v_add_f32_e32 v212, v127, v212
	s_andn2_b64 vcc, exec, s[0:1]
	s_cbranch_vccnz .LBB0_456
	s_and_b32 s0, s34, 2
	s_mulk_i32 s0, 0x4800
	v_add_u32_e32 v128, s0, v245
	v_add_u32_e32 v129, 0x4000, v128
	v_add_u32_e32 v128, 0x6000, v128
	s_waitcnt vmcnt(2)
	ds_write_b128 v225, v[176:179]
	s_waitcnt vmcnt(1)
	ds_write2_b64 v129, v[180:181], v[182:183] offset1:2
	s_waitcnt vmcnt(0)
	ds_write2_b64 v128, v[184:185], v[186:187] offset0:128 offset1:130

; #define FLAS __attribute__((address_space(3)))
; __device__ __forceinline__ void attn_unit_a(FLAS unsigned char* lds, const Unit u) {
;     ...
;         if (i + 2 < NT) { kreg = *(const u32x4*)(ksrc + (size_t)(u.t_lo + i + 2) * 64 * u.ldk);
; #pragma unroll
;             for (int j = 0; j < 2; ++j) vreg[j] = *(const u32x4*)(vsrc + (size_t)j * 64 * MTOK + (u.t_lo + i + 2) * 64); }
;         const int vsp = (i == 0) ? 0 : ((i - 1) & 3);
;         const FLAS unsigned char* vb_ = lds + LA_V + vsp * VBUF + r32 * VPITCH + hi * 16;
;         const FLAS unsigned char* kb = lds + LA_K + ((i + 1) & 1) * KBUF;
;     ...
;         u32x4 vr[3];
; #pragma unroll
;         for (int m = 0; m < 3; ++m) vr[m] = FA_VFRAG(m);
;         const float off = cbC - mrun;
;         FA_SB();
;         float ra, rb, rm;
;         FA_PVM(0); pC0[0] = fadd_s(pC0[0], off); pC1[0] = fadd_s(pC1[0], off); pC0[1] = fadd_s(pC0[1], off); pC1[1] = fadd_s(pC1[1], off); pC0[2] = fadd_s(pC0[2], off); pC1[2] = fadd_s(pC1[2], off); FA_SB();
;         FA_PVM(1); ra = __builtin_fmaxf(__builtin_fmaxf(pC0[0], pC0[1]), pC0[2]); rb = __builtin_fmaxf(__builtin_fmaxf(pC1[0], pC1[1]), pC1[2]); pC0[3] = fadd_s(pC0[3], off); pC1[3] = fadd_s(pC1[3], off); pC0[4] = fadd_s(pC0[4], off); pC1[4] = fadd_s(pC1[4], off); FA_SB();
;         FA_PVM(2); ra = __builtin_fmaxf(__builtin_fmaxf(ra, pC0[3]), pC0[4]); rb = __builtin_fmaxf(__builtin_fmaxf(rb, pC1[3]), pC1[4]); pC0[5] = fadd_s(pC0[5], off); pC1[5] = fadd_s(pC1[5], off); pC0[6] = fadd_s(pC0[6], off); pC1[6] = fadd_s(pC1[6], off); FA_SB();
;         FA_PVM(3); ra = __builtin_fmaxf(__builtin_fmaxf(ra, pC0[5]), pC0[6]); rb = __builtin_fmaxf(__builtin_fmaxf(rb, pC1[5]), pC1[6]); pC0[7] = fadd_s(pC0[7], off); pC1[7] = fadd_s(pC1[7], off); pC0[8] = fadd_s(pC0[8], off); pC1[8] = fadd_s(pC1[8], off); FA_SB();
;         FA_PVM(4); ra = __builtin_fmaxf(__builtin_fmaxf(ra, pC0[7]), pC0[8]); rb = __builtin_fmaxf(__builtin_fmaxf(rb, pC1[7]), pC1[8]); pC0[9] = fadd_s(pC0[9], off); pC1[9] = fadd_s(pC1[9], off); pC0[10] = fadd_s(pC0[10], off); pC1[10] = fadd_s(pC1[10], off); FA_SB();
;         FA_PVM(5); ra = __builtin_fmaxf(__builtin_fmaxf(ra, pC0[9]), pC0[10]); rb = __builtin_fmaxf(__builtin_fmaxf(rb, pC1[9]), pC1[10]); pC0[11] = fadd_s(pC0[11], off); pC1[11] = fadd_s(pC1[11], off); pC0[12] = fadd_s(pC0[12], off); pC1[12] = fadd_s(pC1[12], off); FA_SB();
.LBB0_458:
	s_cmpk_lt_u32 s19, 0x7d
	s_cselect_b64 s[20:21], -1, 0
	s_cmpk_gt_u32 s19, 0x7c
	s_cbranch_scc1 .LBB0_460
	v_add_co_u32_e32 v128, vcc, 0xd690000, v234
	s_nop 1
	v_addc_co_u32_e32 v129, vcc, 0, v235, vcc
	global_load_dwordx4 v[176:179], v[128:129], off
	v_add_co_u32_e32 v128, vcc, 0x13600000, v232
	s_nop 1
	v_addc_co_u32_e32 v129, vcc, 0, v233, vcc
	v_add_co_u32_e32 v130, vcc, 0x13a00000, v232
	s_nop 1
	v_addc_co_u32_e32 v131, vcc, 0, v233, vcc
	global_load_dwordx4 v[180:183], v[128:129], off offset:384
	global_load_dwordx4 v[184:187], v[130:131], off offset:384
.LBB0_460:
	s_and_b32 s0, s19, 2
	s_mulk_i32 s0, 0x4800
	v_add_u32_e32 v201, s0, v251
	v_cvt_pk_bf16_f32 v140, v96, v97
	v_cvt_pk_bf16_f32 v141, v98, v99
	v_cvt_pk_bf16_f32 v142, v100, v101
	v_cvt_pk_bf16_f32 v143, v102, v103
	v_cvt_pk_bf16_f32 v232, v104, v105
	v_cvt_pk_bf16_f32 v233, v106, v107
	ds_read_b128 v[128:131], v201 offset:16384
	ds_read_b128 v[132:135], v201 offset:20992
	ds_read_b128 v[136:139], v201 offset:25600
	v_cvt_pk_bf16_f32 v234, v108, v109
	v_cvt_pk_bf16_f32 v235, v110, v111
	s_waitcnt lgkmcnt(2)
	v_mfma_f32_32x32x16_bf16 v[48:63], v[128:131], v[140:143], v[48:63]
	ds_read_b128 v[128:131], v201 offset:30208
	v_max3_f32 v96, v64, v65, v66
	v_max3_f32 v97, v80, v81, v82
	s_waitcnt lgkmcnt(2)
	v_mfma_f32_32x32x16_bf16 v[32:47], v[132:135], v[140:143], v[32:47]
	ds_read_b128 v[132:135], v201 offset:16416
	v_max3_f32 v96, v96, v67, v68
	v_max3_f32 v97, v97, v83, v84
	s_waitcnt lgkmcnt(2)
	v_mfma_f32_32x32x16_bf16 v[16:31], v[136:139], v[140:143], v[16:31]
	ds_read_b128 v[136:139], v201 offset:21024
	v_max3_f32 v96, v96, v69, v70
	v_max3_f32 v97, v97, v85, v86
	s_waitcnt lgkmcnt(2)
	v_mfma_f32_32x32x16_bf16 v[0:15], v[128:131], v[140:143], v[0:15]
	ds_read_b128 v[128:131], v201 offset:25632
	v_max3_f32 v96, v96, v71, v72
	v_max3_f32 v97, v97, v87, v88
	s_waitcnt lgkmcnt(2)
	v_mfma_f32_32x32x16_bf16 v[48:63], v[132:135], v[232:235], v[48:63]
	ds_read_b128 v[132:135], v201 offset:30240
	v_max3_f32 v96, v96, v73, v74
	v_max3_f32 v97, v97, v89, v90
	s_waitcnt lgkmcnt(2)
	v_mfma_f32_32x32x16_bf16 v[32:47], v[136:139], v[232:235], v[32:47]
	ds_read_b128 v[136:139], v201 offset:16448
	v_max3_f32 v96, v96, v75, v76
	v_max3_f32 v97, v97, v91, v92
	s_waitcnt lgkmcnt(2)
	v_mfma_f32_32x32x16_bf16 v[16:31], v[128:131], v[232:235], v[16:31]
	ds_read_b128 v[128:131], v201 offset:21056
	v_max3_f32 v96, v96, v77, v78
	v_max3_f32 v97, v97, v93, v94
	s_waitcnt lgkmcnt(2)
	v_mfma_f32_32x32x16_bf16 v[0:15], v[132:135], v[232:235], v[0:15]
	ds_read_b128 v[132:135], v201 offset:25664
	v_max3_f32 v96, v96, v97, v79
	v_max_f32_e32 v96, v96, v95
	v_mov_b32_e32 v97, v96
	s_nop 1
	v_permlane32_swap_b32 v96, v97
	s_nop 1
	s_nop 0
	v_max_f32_e32 v96, v96, v97
	v_cmp_lt_f32_e32 vcc, s39, v96
	s_cmp_lg_u64 vcc, 0
	s_cselect_b64 s[0:1], -1, 0
	s_cbranch_vccz .LBB0_462
	v_max_f32_e32 v96, v96, v96
	v_max_f32_e32 v96, 0, v96
	v_exp_f32_e64 v226, -v96
	v_add_f32_e32 v211, v211, v96
	v_sub_f32_e32 v64, v64, v96
	v_sub_f32_e32 v65, v65, v96
	v_mul_f32_e32 v212, v212, v226
	v_sub_f32_e32 v66, v66, v96
	v_sub_f32_e32 v67, v67, v96
	v_sub_f32_e32 v68, v68, v96
	v_sub_f32_e32 v69, v69, v96
	v_sub_f32_e32 v70, v70, v96
	v_sub_f32_e32 v71, v71, v96
	v_sub_f32_e32 v72, v72, v96
	v_sub_f32_e32 v73, v73, v96
	v_sub_f32_e32 v74, v74, v96
	v_sub_f32_e32 v75, v75, v96
	v_sub_f32_e32 v76, v76, v96
	v_sub_f32_e32 v77, v77, v96
	v_sub_f32_e32 v78, v78, v96
	v_sub_f32_e32 v79, v79, v96
	v_sub_f32_e32 v80, v80, v96
	v_sub_f32_e32 v81, v81, v96
	v_sub_f32_e32 v82, v82, v96
	v_sub_f32_e32 v83, v83, v96
	v_sub_f32_e32 v84, v84, v96
	v_sub_f32_e32 v85, v85, v96
	v_sub_f32_e32 v86, v86, v96
	v_sub_f32_e32 v87, v87, v96
	v_sub_f32_e32 v88, v88, v96
	v_sub_f32_e32 v89, v89, v96
	v_sub_f32_e32 v90, v90, v96
	v_sub_f32_e32 v91, v91, v96
	v_sub_f32_e32 v92, v92, v96
	v_sub_f32_e32 v93, v93, v96
	v_sub_f32_e32 v94, v94, v96
	v_sub_f32_e32 v95, v95, v96
.LBB0_462:
	v_cvt_pk_bf16_f32 v140, v112, v113
	v_cvt_pk_bf16_f32 v141, v114, v115
	v_cvt_pk_bf16_f32 v142, v116, v117
	v_cvt_pk_bf16_f32 v143, v118, v119
	v_cvt_pk_bf16_f32 v232, v120, v121
	v_cvt_pk_bf16_f32 v233, v122, v123
	s_waitcnt lgkmcnt(2)
	v_mfma_f32_32x32x16_bf16 v[48:63], v[136:139], v[140:143], v[48:63]
	ds_read_b128 v[136:139], v201 offset:30272
	v_cvt_pk_bf16_f32 v234, v124, v125
	v_cvt_pk_bf16_f32 v235, v126, v127
	v_exp_f32_e32 v64, v64
	v_exp_f32_e32 v65, v65
	s_waitcnt lgkmcnt(2)
	v_mfma_f32_32x32x16_bf16 v[32:47], v[128:131], v[140:143], v[32:47]
	ds_read_b128 v[128:131], v201 offset:16480
	v_exp_f32_e32 v66, v66
	v_exp_f32_e32 v67, v67
	v_add_f32_e32 v212, v64, v212
	v_add_f32_e32 v212, v65, v212
	s_waitcnt lgkmcnt(2)
	v_mfma_f32_32x32x16_bf16 v[16:31], v[132:135], v[140:143], v[16:31]
	ds_read_b128 v[132:135], v201 offset:21088
	v_exp_f32_e32 v68, v68
	v_exp_f32_e32 v69, v69
	v_add_f32_e32 v212, v66, v212
	v_add_f32_e32 v212, v67, v212
	s_waitcnt lgkmcnt(2)
	v_mfma_f32_32x32x16_bf16 v[0:15], v[136:139], v[140:143], v[0:15]
	ds_read_b128 v[136:139], v201 offset:25696
	v_exp_f32_e32 v70, v70
	v_exp_f32_e32 v71, v71
	v_add_f32_e32 v212, v68, v212
	v_add_f32_e32 v212, v69, v212
	s_waitcnt lgkmcnt(2)
	v_mfma_f32_32x32x16_bf16 v[48:63], v[128:131], v[232:235], v[48:63]
	ds_read_b128 v[128:131], v201 offset:30304
	ds_read_b128 v[200:203], v247
	ds_read_b128 v[196:199], v247 offset:512
	ds_read_b128 v[192:195], v248
	ds_read_b128 v[188:191], v248 offset:512
	v_exp_f32_e32 v72, v72
	v_exp_f32_e32 v73, v73
	v_add_f32_e32 v212, v70, v212
	v_add_f32_e32 v212, v71, v212
	s_waitcnt lgkmcnt(6)
	v_mfma_f32_32x32x16_bf16 v[32:47], v[132:135], v[232:235], v[32:47]
	v_exp_f32_e32 v74, v74
	v_exp_f32_e32 v75, v75
	v_add_f32_e32 v212, v72, v212
	v_add_f32_e32 v212, v73, v212
	s_waitcnt lgkmcnt(5)
	v_mfma_f32_32x32x16_bf16 v[16:31], v[136:139], v[232:235], v[16:31]
	v_exp_f32_e32 v76, v76
	v_exp_f32_e32 v77, v77
	v_add_f32_e32 v212, v74, v212
	v_add_f32_e32 v212, v75, v212
	s_waitcnt lgkmcnt(4)
	v_mfma_f32_32x32x16_bf16 v[0:15], v[128:131], v[232:235], v[0:15]
	v_exp_f32_e32 v78, v78
	v_exp_f32_e32 v79, v79
	v_add_f32_e32 v212, v76, v212
	v_add_f32_e32 v212, v77, v212
	s_min_u32 s12, s34, 0x7f
	s_lshl_b32 s12, s12, 6
	s_sub_i32 s14, s12, s47
	s_sub_i32 s15, s14, 31
	s_cmpk_lt_i32 s15, 0x22f
	s_cbranch_scc0 .Lz_plus_o
	s_cmpk_gt_i32 s14, 0xfd92
	s_cbranch_scc1 .Lgather_o
	v_sub_f32_e32 v126, s100, v211
	s_branch .Lz_chk_o
; #define FLAS __attribute__((address_space(3)))
; #define FA_SB() __builtin_amdgcn_sched_barrier(0)
; #define FA_EXP2(J, PX, R) do { const float e0_ = __builtin_amdgcn_exp2f(PX[R]), e1_ = __builtin_amdgcn_exp2f(PX[(R) + 1]); ps += e0_; ps += e1_; PWN[(J) >> 2][(J) & 3] = cvtpk(e0_, e1_); } while (0)
; __device__ __forceinline__ void attn_unit_a(FLAS unsigned char* lds, const Unit u) {
;     ...
;         float cbN; bool ziN; const int inx = (i + 1 < NT) ? i + 1 : NT - 1;
;         FA_BIAS(inx, pN0, pN1, cbN, ziN);
;         FA_SB();
;         if (ziN) { pN0 = __builtin_amdgcn_mfma_f32_32x32x16_bf16(kf[0], qr[0], z16, 0, 0, 0); FA_EXP2(8, pC1, 0); FA_SB(); pN1 = __builtin_amdgcn_mfma_f32_32x32x16_bf16(kf[1], qr[0], z16, 0, 0, 0); }
;         else { pN0 = __builtin_amdgcn_mfma_f32_32x32x16_bf16(kf[0], qr[0], pN0, 0, 0, 0); FA_EXP2(8, pC1, 0); FA_SB(); pN1 = __builtin_amdgcn_mfma_f32_32x32x16_bf16(kf[1], qr[0], pN1, 0, 0, 0); }
;         kf[0] = FA_KF(2, 0); kf[1] = FA_KF(2, 1); FA_EXP2(9, pC1, 2); FA_SB();
;         pN0 = __builtin_amdgcn_mfma_f32_32x32x16_bf16(kf[2], qr[1], pN0, 0, 0, 0); FA_EXP2(10, pC1, 4); FA_SB();
;         pN1 = __builtin_amdgcn_mfma_f32_32x32x16_bf16(kf[3], qr[1], pN1, 0, 0, 0); kf[2] = FA_KF(3, 0); kf[3] = FA_KF(3, 1); FA_EXP2(11, pC1, 6); FA_SB();
;         pN0 = __builtin_amdgcn_mfma_f32_32x32x16_bf16(kf[0], qr[2], pN0, 0, 0, 0); FA_EXP2(12, pC1, 8); FA_SB();
;         pN1 = __builtin_amdgcn_mfma_f32_32x32x16_bf16(kf[1], qr[2], pN1, 0, 0, 0); FA_EXP2(13, pC1, 10); FA_SB();
;         pN0 = __builtin_amdgcn_mfma_f32_32x32x16_bf16(kf[2], qr[3], pN0, 0, 0, 0); FA_EXP2(14, pC1, 12); FA_SB();
;         pN1 = __builtin_amdgcn_mfma_f32_32x32x16_bf16(kf[3], qr[3], pN1, 0, 0, 0); FA_EXP2(15, pC1, 14); FA_SB();
;     ...
;         lsum += ps; cbC = cbN;
;         if (i + 2 < NT) { *(FLAS u32x4*)(lds + LA_K + (i & 1) * KBUF + kdst) = kreg;
; #pragma unroll
;             for (int j = 0; j < 2; ++j) { *(FLAS u32x2*)(lds + LA_V + ((i + 2) & 3) * VBUF + vdst + j * 64 * VPITCH) = (u32x2){vreg[j].x, vreg[j].y}; *(FLAS u32x2*)(lds + LA_V + ((i + 2) & 3) * VBUF + vdst + j * 64 * VPITCH + 16) = (u32x2){vreg[j].z, vreg[j].w}; } }
.Lz_plus_o:
	v_sub_f32_e32 v126, s101, v211
.Lz_chk_o:
	v_cmp_neq_f32_e32 vcc, v126, v144
	s_cbranch_vccz .Lz_go_o
	v_mov_b32_e32 v144, v126
	v_mov_b32_e32 v145, v126
	v_mov_b32_e32 v146, v126
	v_mov_b32_e32 v147, v126
	v_mov_b32_e32 v148, v126
	v_mov_b32_e32 v149, v126
	v_mov_b32_e32 v150, v126
	v_mov_b32_e32 v151, v126
	v_mov_b32_e32 v152, v126
	v_mov_b32_e32 v153, v126
	v_mov_b32_e32 v154, v126
	v_mov_b32_e32 v155, v126
	v_mov_b32_e32 v156, v126
	v_mov_b32_e32 v157, v126
	v_mov_b32_e32 v158, v126
	v_mov_b32_e32 v159, v126
	s_nop 1
.Lz_go_o:
	s_waitcnt lgkmcnt(0)
	v_mfma_f32_32x32x16_bf16 v[96:111], v[200:203], v[160:163], v[144:159]
	v_exp_f32_e32 v80, v80
	v_exp_f32_e32 v81, v81
	v_add_f32_e32 v212, v78, v212
	v_add_f32_e32 v212, v79, v212
	v_mfma_f32_32x32x16_bf16 v[112:127], v[196:199], v[160:163], v[144:159]
	v_exp_f32_e32 v82, v82
	v_exp_f32_e32 v83, v83
	v_add_f32_e32 v212, v80, v212
	v_add_f32_e32 v212, v81, v212
	s_branch .Lk2_o
.Lgather_o:
	v_sub_u32_e32 v96, s12, v244
	v_lshl_add_u32 v108, v96, 2, v240
	v_add_u32_e32 v96, 0x1500, v108
	v_add_u32_e32 v98, 0x1580, v108
	v_add_u32_e32 v99, 0x1508, v108
	v_add_u32_e32 v100, 0x1588, v108
	ds_read2_b32 v[96:97], v96 offset1:1
	ds_read2_b32 v[112:113], v98 offset1:1
	ds_read2_b32 v[98:99], v99 offset1:1
	ds_read2_b32 v[114:115], v100 offset1:1
	v_add_u32_e32 v100, 0x1520, v108
	v_add_u32_e32 v102, 0x15a0, v108
	v_add_u32_e32 v103, 0x1528, v108
	v_add_u32_e32 v104, 0x15a8, v108
	ds_read2_b32 v[100:101], v100 offset1:1
	ds_read2_b32 v[116:117], v102 offset1:1
	ds_read2_b32 v[102:103], v103 offset1:1
	ds_read2_b32 v[118:119], v104 offset1:1
	v_add_u32_e32 v104, 0x1540, v108
	v_add_u32_e32 v106, 0x15c0, v108
	v_add_u32_e32 v107, 0x1548, v108
	v_add_u32_e32 v109, 0x15c8, v108
	ds_read2_b32 v[104:105], v104 offset1:1
	ds_read2_b32 v[120:121], v106 offset1:1
	ds_read2_b32 v[106:107], v107 offset1:1
	ds_read2_b32 v[122:123], v109 offset1:1
	v_add_u32_e32 v109, 0x1560, v108
	v_add_u32_e32 v110, 0x15e0, v108
	v_add_u32_e32 v111, 0x1568, v108
	v_add_u32_e32 v126, 0x15e8, v108
	ds_read2_b32 v[108:109], v109 offset1:1
	ds_read2_b32 v[124:125], v110 offset1:1
	ds_read2_b32 v[110:111], v111 offset1:1
	ds_read2_b32 v[126:127], v126 offset1:1
	s_waitcnt lgkmcnt(0)
	v_sub_f32_e32 v96, v96, v211
	v_sub_f32_e32 v97, v97, v211
	v_sub_f32_e32 v98, v98, v211
	v_sub_f32_e32 v99, v99, v211
	v_sub_f32_e32 v100, v100, v211
	v_sub_f32_e32 v101, v101, v211
	v_sub_f32_e32 v102, v102, v211
	v_sub_f32_e32 v103, v103, v211
	v_sub_f32_e32 v104, v104, v211
	v_sub_f32_e32 v105, v105, v211
	v_sub_f32_e32 v106, v106, v211
	v_sub_f32_e32 v107, v107, v211
	v_sub_f32_e32 v108, v108, v211
	v_sub_f32_e32 v109, v109, v211
	v_sub_f32_e32 v110, v110, v211
	v_sub_f32_e32 v111, v111, v211
	v_sub_f32_e32 v112, v112, v211
	v_sub_f32_e32 v113, v113, v211
	v_sub_f32_e32 v114, v114, v211
	v_sub_f32_e32 v115, v115, v211
	v_sub_f32_e32 v116, v116, v211
	v_sub_f32_e32 v117, v117, v211
	v_sub_f32_e32 v118, v118, v211
	v_sub_f32_e32 v119, v119, v211
	v_sub_f32_e32 v120, v120, v211
	v_sub_f32_e32 v121, v121, v211
	v_sub_f32_e32 v122, v122, v211
	v_sub_f32_e32 v123, v123, v211
	v_sub_f32_e32 v124, v124, v211
	v_sub_f32_e32 v125, v125, v211
	v_sub_f32_e32 v126, v126, v211
	v_sub_f32_e32 v127, v127, v211
	s_nop 1
	v_mfma_f32_32x32x16_bf16 v[96:111], v[200:203], v[160:163], v[96:111]
	v_exp_f32_e32 v80, v80
	v_exp_f32_e32 v81, v81
	v_add_f32_e32 v212, v78, v212
	v_add_f32_e32 v212, v79, v212
	v_mfma_f32_32x32x16_bf16 v[112:127], v[196:199], v[160:163], v[112:127]
	v_exp_f32_e32 v82, v82
	v_exp_f32_e32 v83, v83
	v_add_f32_e32 v212, v80, v212
	v_add_f32_e32 v212, v81, v212
.Lk2_o:
	ds_read_b128 v[128:131], v249
	ds_read_b128 v[132:135], v249 offset:512
	v_mfma_f32_32x32x16_bf16 v[96:111], v[192:195], v[164:167], v[96:111]
	v_exp_f32_e32 v84, v84
	v_exp_f32_e32 v85, v85
	v_add_f32_e32 v212, v82, v212
	v_add_f32_e32 v212, v83, v212
	v_mfma_f32_32x32x16_bf16 v[112:127], v[188:191], v[164:167], v[112:127]
	ds_read_b128 v[136:139], v250
	ds_read_b128 v[140:143], v250 offset:512
	v_exp_f32_e32 v86, v86
	v_exp_f32_e32 v87, v87
	v_add_f32_e32 v212, v84, v212
	v_add_f32_e32 v212, v85, v212
	s_waitcnt lgkmcnt(3)
	v_mfma_f32_32x32x16_bf16 v[96:111], v[128:131], v[168:171], v[96:111]
	v_exp_f32_e32 v88, v88
	v_exp_f32_e32 v89, v89
	v_add_f32_e32 v212, v86, v212
	v_add_f32_e32 v212, v87, v212
	s_waitcnt lgkmcnt(2)
	v_mfma_f32_32x32x16_bf16 v[112:127], v[132:135], v[168:171], v[112:127]
	v_exp_f32_e32 v90, v90
	v_exp_f32_e32 v91, v91
	v_add_f32_e32 v212, v88, v212
	v_add_f32_e32 v212, v89, v212
	s_waitcnt lgkmcnt(1)
	v_mfma_f32_32x32x16_bf16 v[96:111], v[136:139], v[172:175], v[96:111]
	v_exp_f32_e32 v92, v92
	v_exp_f32_e32 v93, v93
	v_add_f32_e32 v212, v90, v212
	v_add_f32_e32 v212, v91, v212
	s_waitcnt lgkmcnt(0)
	v_mfma_f32_32x32x16_bf16 v[112:127], v[140:143], v[172:175], v[112:127]
	v_exp_f32_e32 v94, v94
	v_exp_f32_e32 v95, v95
	v_add_f32_e32 v212, v92, v212
	v_add_f32_e32 v212, v93, v212
	v_add_f32_e32 v212, v94, v212
	v_add_f32_e32 v212, v95, v212
	s_andn2_b64 vcc, exec, s[20:21]
	s_cbranch_vccnz .LBB0_476
	v_add_u32_e32 v128, s18, v245
	v_add_u32_e32 v129, 0x4000, v128
	v_add_u32_e32 v128, 0x6000, v128
	s_waitcnt vmcnt(2)
	ds_write_b128 v225, v[176:179] offset:8192
	s_waitcnt vmcnt(1)
	ds_write2_b64 v129, v[180:181], v[182:183] offset1:2
	s_waitcnt vmcnt(0)
	ds_write2_b64 v128, v[184:185], v[186:187] offset0:128 offset1:130
; #define FLAS __attribute__((address_space(3)))
; __device__ __forceinline__ float xhalf_sum(float m) { unsigned a = __builtin_bit_cast(unsigned, m), b = a; xswap(a, b); return __builtin_bit_cast(float, a) + __builtin_bit_cast(float, b); }
; __device__ __forceinline__ void attn_unit_a(FLAS unsigned char* lds, const Unit u) {
;     ...
;         lsum += ps; cbC = cbN;
;         if (i + 2 < NT) { *(FLAS u32x4*)(lds + LA_K + (i & 1) * KBUF + kdst) = kreg;
; #pragma unroll
;             for (int j = 0; j < 2; ++j) { *(FLAS u32x2*)(lds + LA_V + ((i + 2) & 3) * VBUF + vdst + j * 64 * VPITCH) = (u32x2){vreg[j].x, vreg[j].y}; *(FLAS u32x2*)(lds + LA_V + ((i + 2) & 3) * VBUF + vdst + j * 64 * VPITCH + 16) = (u32x2){vreg[j].z, vreg[j].w}; } }
;         __syncthreads();
;     };
;     for (int i = 0; i < NT; i += 2) { step(i, pa0, pa1, pb0, pb1, pwa, pwb); if (i + 1 < NT) step(i + 1, pb0, pb1, pa0, pa1, pwb, pwa); }
;     if (pend) {
; #pragma unroll
;         for (int d = 0; d < NDB; ++d) o[d] = o[d] * fpend; }
;     if (NT & 1) { FA_PVP((NT - 1) & 3, pwb); } else { FA_PVP((NT - 1) & 3, pwa); }
;     ...
;     const float inv = 1.0f / xhalf_sum(lsum);
;     bf16_t* op = u.O + (size_t)(u.tok0 + q) * u.ldo + 4 * hi;
.LBB0_476:
	v_cvt_pk_bf16_f32 v192, v80, v81
	s_mov_b64 s[14:15], 0x100
	v_lshl_add_u64 v[228:229], v[228:229], 0, s[14:15]
	v_cvt_pk_bf16_f32 v193, v82, v83
	s_mov_b64 s[14:15], 0x60000
	v_cvt_pk_bf16_f32 v206, v68, v69
	v_cvt_pk_bf16_f32 v194, v84, v85
	v_cvt_pk_bf16_f32 v207, v70, v71
	v_cvt_pk_bf16_f32 v196, v72, v73
	v_cvt_pk_bf16_f32 v195, v86, v87
	v_cvt_pk_bf16_f32 v197, v74, v75
	v_cvt_pk_bf16_f32 v198, v76, v77
	v_cvt_pk_bf16_f32 v188, v88, v89
	v_cvt_pk_bf16_f32 v199, v78, v79
	s_addk_i32 s48, 0x80
	v_cvt_pk_bf16_f32 v189, v90, v91
	s_addk_i32 s49, 0x200
	v_lshl_add_u64 v[230:231], v[230:231], 0, s[14:15]
	v_cvt_pk_bf16_f32 v190, v92, v93
	s_mov_b64 s[24:25], 0
	s_and_b64 vcc, exec, s[4:5]
	v_cvt_pk_bf16_f32 v191, v94, v95
	v_cvt_pk_bf16_f32 v204, v64, v65
	v_cvt_pk_bf16_f32 v205, v66, v67
	s_waitcnt lgkmcnt(0)
	s_barrier
	s_cbranch_vccz .LBB0_433
	s_andn2_b64 vcc, exec, s[0:1]
	s_cbranch_vccnz .LBB0_479
	v_pk_mul_f32 v[62:63], v[62:63], v[226:227] op_sel_hi:[1,0]
	v_pk_mul_f32 v[60:61], v[60:61], v[226:227] op_sel_hi:[1,0]
	v_pk_mul_f32 v[58:59], v[58:59], v[226:227] op_sel_hi:[1,0]
	v_pk_mul_f32 v[56:57], v[56:57], v[226:227] op_sel_hi:[1,0]
	v_pk_mul_f32 v[54:55], v[54:55], v[226:227] op_sel_hi:[1,0]
	v_pk_mul_f32 v[52:53], v[52:53], v[226:227] op_sel_hi:[1,0]
	v_pk_mul_f32 v[50:51], v[50:51], v[226:227] op_sel_hi:[1,0]
	v_pk_mul_f32 v[48:49], v[48:49], v[226:227] op_sel_hi:[1,0]
	v_pk_mul_f32 v[46:47], v[46:47], v[226:227] op_sel_hi:[1,0]
	v_pk_mul_f32 v[44:45], v[44:45], v[226:227] op_sel_hi:[1,0]
	v_pk_mul_f32 v[42:43], v[42:43], v[226:227] op_sel_hi:[1,0]
	v_pk_mul_f32 v[40:41], v[40:41], v[226:227] op_sel_hi:[1,0]
	v_pk_mul_f32 v[38:39], v[38:39], v[226:227] op_sel_hi:[1,0]
	v_pk_mul_f32 v[36:37], v[36:37], v[226:227] op_sel_hi:[1,0]
	v_pk_mul_f32 v[34:35], v[34:35], v[226:227] op_sel_hi:[1,0]
	v_pk_mul_f32 v[32:33], v[32:33], v[226:227] op_sel_hi:[1,0]
	v_pk_mul_f32 v[30:31], v[30:31], v[226:227] op_sel_hi:[1,0]
	v_pk_mul_f32 v[28:29], v[28:29], v[226:227] op_sel_hi:[1,0]
	v_pk_mul_f32 v[26:27], v[26:27], v[226:227] op_sel_hi:[1,0]
	v_pk_mul_f32 v[24:25], v[24:25], v[226:227] op_sel_hi:[1,0]
	v_pk_mul_f32 v[22:23], v[22:23], v[226:227] op_sel_hi:[1,0]
	v_pk_mul_f32 v[20:21], v[20:21], v[226:227] op_sel_hi:[1,0]
	v_pk_mul_f32 v[18:19], v[18:19], v[226:227] op_sel_hi:[1,0]
	v_pk_mul_f32 v[16:17], v[16:17], v[226:227] op_sel_hi:[1,0]
	v_pk_mul_f32 v[14:15], v[14:15], v[226:227] op_sel_hi:[1,0]
	v_pk_mul_f32 v[12:13], v[12:13], v[226:227] op_sel_hi:[1,0]
	v_pk_mul_f32 v[10:11], v[10:11], v[226:227] op_sel_hi:[1,0]
	v_pk_mul_f32 v[8:9], v[8:9], v[226:227] op_sel_hi:[1,0]
	v_pk_mul_f32 v[6:7], v[6:7], v[226:227] op_sel_hi:[1,0]
	v_pk_mul_f32 v[4:5], v[4:5], v[226:227] op_sel_hi:[1,0]
	v_pk_mul_f32 v[2:3], v[2:3], v[226:227] op_sel_hi:[1,0]
	v_pk_mul_f32 v[0:1], v[0:1], v[226:227] op_sel_hi:[1,0]
.LBB0_479:
	v_readlane_b32 s12, v254, 48
	s_lshl_b32 s0, s26, 1
	s_add_u32 s0, s16, s0
	v_add3_u32 v82, s12, v246, v224
	ds_read_b128 v[64:67], v82
	ds_read_b128 v[68:71], v82 offset:4608
	ds_read_b128 v[72:75], v82 offset:9216
	ds_read_b128 v[76:79], v82 offset:13824
	s_addc_u32 s1, s17, 0
	s_cmp_eq_u32 s44, 0
	v_mov_b32_e32 v240, v213
	s_cselect_b32 s4, s0, s45
	s_cselect_b32 s5, s1, s46
	s_movk_i32 s12, 0x200
	s_cselect_b32 s12, s12, 0x600
	s_cmp_lg_u32 s44, 0
	v_mov_b32_e32 v80, s4
	v_mov_b32_e32 v81, s5
	s_waitcnt lgkmcnt(3)
	v_mfma_f32_32x32x16_bf16 v[48:63], v[64:67], v[204:207], v[48:63]
	ds_read_b128 v[64:67], v82 offset:32
	s_waitcnt lgkmcnt(3)
	v_mfma_f32_32x32x16_bf16 v[32:47], v[68:71], v[204:207], v[32:47]
	ds_read_b128 v[68:71], v82 offset:4640
	s_waitcnt lgkmcnt(3)
	v_mfma_f32_32x32x16_bf16 v[16:31], v[72:75], v[204:207], v[16:31]
	ds_read_b128 v[72:75], v82 offset:9248
	s_waitcnt lgkmcnt(3)
	v_mfma_f32_32x32x16_bf16 v[0:15], v[76:79], v[204:207], v[0:15]
	ds_read_b128 v[76:79], v82 offset:13856
	s_waitcnt lgkmcnt(3)
	v_mfma_f32_32x32x16_bf16 v[48:63], v[64:67], v[196:199], v[48:63]
	ds_read_b128 v[64:67], v82 offset:64
	s_waitcnt lgkmcnt(3)
	v_mfma_f32_32x32x16_bf16 v[32:47], v[68:71], v[196:199], v[32:47]
	ds_read_b128 v[68:71], v82 offset:4672
	s_waitcnt lgkmcnt(3)
	v_mfma_f32_32x32x16_bf16 v[16:31], v[72:75], v[196:199], v[16:31]
	ds_read_b128 v[72:75], v82 offset:9280
	s_waitcnt lgkmcnt(3)
	v_mfma_f32_32x32x16_bf16 v[0:15], v[76:79], v[196:199], v[0:15]
	ds_read_b128 v[76:79], v82 offset:13888
	s_waitcnt lgkmcnt(3)
	v_mfma_f32_32x32x16_bf16 v[48:63], v[64:67], v[192:195], v[48:63]
	ds_read_b128 v[64:67], v82 offset:96
	s_waitcnt lgkmcnt(3)
	v_mfma_f32_32x32x16_bf16 v[32:47], v[68:71], v[192:195], v[32:47]
	ds_read_b128 v[68:71], v82 offset:4704
	s_waitcnt lgkmcnt(3)
	v_mfma_f32_32x32x16_bf16 v[16:31], v[72:75], v[192:195], v[16:31]
	ds_read_b128 v[72:75], v82 offset:9312
	s_waitcnt lgkmcnt(3)
	v_mfma_f32_32x32x16_bf16 v[0:15], v[76:79], v[192:195], v[0:15]
	ds_read_b128 v[76:79], v82 offset:13920
	s_waitcnt lgkmcnt(3)
	v_mfma_f32_32x32x16_bf16 v[48:63], v[64:67], v[188:191], v[48:63]
	s_waitcnt lgkmcnt(2)
	v_mfma_f32_32x32x16_bf16 v[32:47], v[68:71], v[188:191], v[32:47]
	s_waitcnt lgkmcnt(1)
	v_mfma_f32_32x32x16_bf16 v[16:31], v[72:75], v[188:191], v[16:31]
	s_waitcnt lgkmcnt(0)
	v_mfma_f32_32x32x16_bf16 v[0:15], v[76:79], v[188:191], v[0:15]
	v_mov_b32_e32 v64, v212
	s_nop 1
	v_permlane32_swap_b32 v212, v64
	s_nop 1
	v_lshlrev_b32_e32 v208, 3, v243
	v_add_f32_e32 v64, v212, v64
	v_div_scale_f32 v65, s[4:5], v64, v64, 1.0
	v_rcp_f32_e32 v66, v65
	v_div_scale_f32 v67, vcc, 1.0, v64, 1.0
	v_mov_b32_e32 v244, v227
	v_fma_f32 v68, -v65, v66, 1.0
	v_fmac_f32_e32 v66, v68, v66
	v_mul_f32_e32 v68, v67, v66
	v_fma_f32 v69, -v65, v68, v67
	v_fmac_f32_e32 v68, v69, v66
	v_fma_f32 v65, -v65, v68, v67
	v_div_fmas_f32 v65, v65, v66, v68
	v_div_fixup_f32 v66, v65, v64, 1.0
	v_mad_i64_i32 v[64:65], s[4:5], s12, v222, 0
	v_lshl_add_u64 v[64:65], v[64:65], 1, v[80:81]
	v_lshl_add_u64 v[64:65], v[64:65], 0, v[208:209]
	s_mov_b64 s[4:5], -1
	s_cbranch_scc0 .LBB0_481
; __device__ __forceinline__ float xhalf_sum(float m) { unsigned a = __builtin_bit_cast(unsigned, m), b = a; xswap(a, b); return __builtin_bit_cast(float, a) + __builtin_bit_cast(float, b); }
; __device__ __forceinline__ void attn_unit_a(FLAS unsigned char* lds, const Unit u) {
;     ...
;     if (u.comb) {
;         const float lam = *u.lamp, gsc = 1.0f - u.lam_init;
;         const bf16_t* o1p = u.O1 + (size_t)(u.tok0 + q) * 512 + 4 * hi;
;         float ss = 0.f;
; #pragma unroll
;         for (int db = 0; db < NDB; ++db)
; #pragma unroll
;             for (int g = 0; g < 4; ++g) {
;                 const unsigned long long w = __hip_atomic_load((const unsigned long long*)(o1p + db * 32 + 8 * g), __ATOMIC_RELAXED, __HIP_MEMORY_SCOPE_AGENT);
;                 const unsigned w0 = (unsigned)w, w1 = (unsigned)(w >> 32);
;                 const float a0 = __builtin_bit_cast(float, w0 << 16), a1 = __builtin_bit_cast(float, w0 & 0xffff0000u), a2 = __builtin_bit_cast(float, w1 << 16), a3 = __builtin_bit_cast(float, w1 & 0xffff0000u);
;                 const float x0 = a0 - lam * (o[db][4 * g] * inv), x1 = a1 - lam * (o[db][4 * g + 1] * inv), x2 = a2 - lam * (o[db][4 * g + 2] * inv), x3 = a3 - lam * (o[db][4 * g + 3] * inv);
;                 o[db][4 * g] = x0; o[db][4 * g + 1] = x1; o[db][4 * g + 2] = x2; o[db][4 * g + 3] = x3; ss += (x0 * x0 + x1 * x1) + (x2 * x2 + x3 * x3); }
;         const float rr = 1.0f / sqrtf(xhalf_sum(ss) * (1.f / 128.f) + 1e-6f) * gsc;
	v_lshlrev_b32_e32 v67, 2, v243
	v_lshlrev_b64 v[68:69], 10, v[222:223]
	v_lshl_add_u64 v[68:69], s[0:1], 0, v[68:69]
	v_lshlrev_b32_e32 v208, 1, v67
	v_lshl_add_u64 v[68:69], v[68:69], 0, v[208:209]
	global_load_dword v70, v209, s[6:7]
	global_load_dwordx2 v[72:73], v[68:69], off sc1
	global_load_dwordx2 v[74:75], v[68:69], off offset:16 sc1
	global_load_dwordx2 v[76:77], v[68:69], off offset:32 sc1
	global_load_dwordx2 v[78:79], v[68:69], off offset:48 sc1
	global_load_dwordx2 v[80:81], v[68:69], off offset:64 sc1
	global_load_dwordx2 v[82:83], v[68:69], off offset:80 sc1
	global_load_dwordx2 v[84:85], v[68:69], off offset:96 sc1
	global_load_dwordx2 v[86:87], v[68:69], off offset:112 sc1
	global_load_dwordx2 v[88:89], v[68:69], off offset:128 sc1
	global_load_dwordx2 v[90:91], v[68:69], off offset:144 sc1
	global_load_dwordx2 v[92:93], v[68:69], off offset:160 sc1
	global_load_dwordx2 v[94:95], v[68:69], off offset:176 sc1
	global_load_dwordx2 v[96:97], v[68:69], off offset:192 sc1
	global_load_dwordx2 v[98:99], v[68:69], off offset:208 sc1
	global_load_dwordx2 v[100:101], v[68:69], off offset:224 sc1
	s_nop 0
	global_load_dwordx2 v[68:69], v[68:69], off offset:240 sc1
	v_lshlrev_b32_e32 v67, 2, v67
	s_waitcnt vmcnt(15)
	v_lshlrev_b32_e32 v102, 16, v72
	v_and_b32_e32 v103, 0xffff0000, v72
	v_lshlrev_b32_e32 v72, 16, v73
	s_waitcnt vmcnt(12)
	v_lshlrev_b32_e32 v108, 16, v78
	v_and_b32_e32 v109, 0xffff0000, v78
	v_lshlrev_b32_e32 v110, 16, v79
	v_and_b32_e32 v111, 0xffff0000, v79
	v_pk_mul_f32 v[78:79], v[14:15], v[66:67] op_sel_hi:[1,0]
	v_and_b32_e32 v73, 0xffff0000, v73
	s_waitcnt vmcnt(9)
	v_lshlrev_b32_e32 v142, 16, v84
	v_and_b32_e32 v143, 0xffff0000, v84
	v_lshlrev_b32_e32 v144, 16, v85
	v_and_b32_e32 v145, 0xffff0000, v85
	v_lshlrev_b32_e32 v116, 16, v80
	v_and_b32_e32 v117, 0xffff0000, v80
	s_waitcnt vmcnt(0)
	v_lshlrev_b32_e32 v114, 16, v68
	v_and_b32_e32 v115, 0xffff0000, v68
	v_lshlrev_b32_e32 v68, 16, v69
	v_and_b32_e32 v69, 0xffff0000, v69
	v_pk_fma_f32 v[68:69], v[78:79], v[70:71], v[68:69] op_sel_hi:[1,0,1] neg_lo:[1,0,0] neg_hi:[1,0,0]
	v_pk_mul_f32 v[78:79], v[50:51], v[66:67] op_sel_hi:[1,0]
	v_lshlrev_b32_e32 v104, 16, v74
	v_pk_fma_f32 v[72:73], v[78:79], v[70:71], v[72:73] op_sel_hi:[1,0,1] neg_lo:[1,0,0] neg_hi:[1,0,0]
	v_and_b32_e32 v105, 0xffff0000, v74
	v_mul_f32_e32 v78, v73, v73
	v_pk_fma_f32 v[84:85], v[72:73], v[72:73], v[78:79] op_sel_hi:[1,1,0]
	v_pk_mul_f32 v[78:79], v[48:49], v[66:67] op_sel_hi:[1,0]
	v_lshlrev_b32_e32 v74, 16, v75
	v_pk_fma_f32 v[78:79], v[78:79], v[70:71], v[102:103] op_sel_hi:[1,0,1] neg_lo:[1,0,0] neg_hi:[1,0,0]
	v_and_b32_e32 v75, 0xffff0000, v75
	v_mul_f32_e32 v80, v79, v79
	v_lshlrev_b32_e32 v136, 16, v81
	v_and_b32_e32 v137, 0xffff0000, v81
	v_lshlrev_b32_e32 v146, 16, v86
	v_and_b32_e32 v147, 0xffff0000, v86
	v_lshlrev_b32_e32 v148, 16, v87
	v_and_b32_e32 v149, 0xffff0000, v87
	v_pk_fma_f32 v[86:87], v[78:79], v[78:79], v[80:81] op_sel_hi:[1,1,0]
	v_pk_mul_f32 v[80:81], v[54:55], v[66:67] op_sel_hi:[1,0]
	v_lshlrev_b32_e32 v150, 16, v88
	v_pk_fma_f32 v[74:75], v[80:81], v[70:71], v[74:75] op_sel_hi:[1,0,1] neg_lo:[1,0,0] neg_hi:[1,0,0]
	v_and_b32_e32 v151, 0xffff0000, v88
	v_mul_f32_e32 v80, v75, v75
	v_lshlrev_b32_e32 v152, 16, v89
	v_and_b32_e32 v153, 0xffff0000, v89
	v_pk_fma_f32 v[88:89], v[74:75], v[74:75], v[80:81] op_sel_hi:[1,1,0]
	v_pk_mul_f32 v[80:81], v[52:53], v[66:67] op_sel_hi:[1,0]
	v_lshlrev_b32_e32 v138, 16, v82
	v_pk_fma_f32 v[80:81], v[80:81], v[70:71], v[104:105] op_sel_hi:[1,0,1] neg_lo:[1,0,0] neg_hi:[1,0,0]
	v_and_b32_e32 v139, 0xffff0000, v82
	v_mul_f32_e32 v82, v81, v81
	v_lshlrev_b32_e32 v106, 16, v76
	v_and_b32_e32 v107, 0xffff0000, v76
	v_lshlrev_b32_e32 v76, 16, v77
	v_and_b32_e32 v77, 0xffff0000, v77
	v_lshlrev_b32_e32 v140, 16, v83
	v_and_b32_e32 v141, 0xffff0000, v83
	v_lshlrev_b32_e32 v154, 16, v90
	v_and_b32_e32 v155, 0xffff0000, v90
	v_lshlrev_b32_e32 v156, 16, v91
	v_and_b32_e32 v157, 0xffff0000, v91
	v_pk_fma_f32 v[90:91], v[80:81], v[80:81], v[82:83] op_sel_hi:[1,1,0]
	v_pk_mul_f32 v[82:83], v[58:59], v[66:67] op_sel_hi:[1,0]
	v_lshlrev_b32_e32 v118, 16, v92
	v_pk_fma_f32 v[76:77], v[82:83], v[70:71], v[76:77] op_sel_hi:[1,0,1] neg_lo:[1,0,0] neg_hi:[1,0,0]
	v_pk_mul_f32 v[82:83], v[56:57], v[66:67] op_sel_hi:[1,0]
	v_and_b32_e32 v119, 0xffff0000, v92
	v_pk_fma_f32 v[82:83], v[82:83], v[70:71], v[106:107] op_sel_hi:[1,0,1] neg_lo:[1,0,0] neg_hi:[1,0,0]
	v_lshlrev_b32_e32 v158, 16, v93
	v_and_b32_e32 v159, 0xffff0000, v93
	v_lshlrev_b32_e32 v122, 16, v94
	v_and_b32_e32 v123, 0xffff0000, v94
	v_lshlrev_b32_e32 v112, 16, v95
	v_and_b32_e32 v113, 0xffff0000, v95
	v_pk_mul_f32 v[92:93], v[76:77], v[76:77]
	v_pk_mul_f32 v[94:95], v[82:83], v[82:83]
	v_mov_b32_e32 v91, v92
	v_mov_b32_e32 v89, v93
	v_mov_b32_e32 v87, v94
	v_mov_b32_e32 v85, v95
	v_pk_add_f32 v[88:89], v[90:91], v[88:89]
	v_pk_add_f32 v[84:85], v[86:87], v[84:85]
	v_lshlrev_b32_e32 v132, 16, v96
	v_pk_add_f32 v[84:85], v[84:85], v[88:89]
	v_and_b32_e32 v133, 0xffff0000, v96
	v_lshlrev_b32_e32 v124, 16, v97
	v_and_b32_e32 v125, 0xffff0000, v97
	v_pk_add_f32 v[96:97], v[84:85], v[84:85] op_sel:[0,1] op_sel_hi:[1,0]
	v_pk_mul_f32 v[84:85], v[62:63], v[66:67] op_sel_hi:[1,0]
	v_pk_mul_f32 v[86:87], v[60:61], v[66:67] op_sel_hi:[1,0]
	v_pk_fma_f32 v[84:85], v[84:85], v[70:71], v[110:111] op_sel_hi:[1,0,1] neg_lo:[1,0,0] neg_hi:[1,0,0]
	v_pk_fma_f32 v[90:91], v[86:87], v[70:71], v[108:109] op_sel_hi:[1,0,1] neg_lo:[1,0,0] neg_hi:[1,0,0]
	v_mov_b32_e32 v89, v85
	v_mov_b32_e32 v88, v91
	v_mov_b32_e32 v86, v90
	v_mov_b32_e32 v87, v84
	v_pk_mul_f32 v[88:89], v[88:89], v[88:89]
; __device__ __forceinline__ void attn_unit_a(FLAS unsigned char* lds, const Unit u) {
;     ...
; #pragma unroll
;         for (int db = 0; db < NDB; ++db)
; #pragma unroll
;             for (int g = 0; g < 4; ++g) {
;                 const unsigned long long w = __hip_atomic_load((const unsigned long long*)(o1p + db * 32 + 8 * g), __ATOMIC_RELAXED, __HIP_MEMORY_SCOPE_AGENT);
;                 const unsigned w0 = (unsigned)w, w1 = (unsigned)(w >> 32);
;                 const float a0 = __builtin_bit_cast(float, w0 << 16), a1 = __builtin_bit_cast(float, w0 & 0xffff0000u), a2 = __builtin_bit_cast(float, w1 << 16), a3 = __builtin_bit_cast(float, w1 & 0xffff0000u);
;                 const float x0 = a0 - lam * (o[db][4 * g] * inv), x1 = a1 - lam * (o[db][4 * g + 1] * inv), x2 = a2 - lam * (o[db][4 * g + 2] * inv), x3 = a3 - lam * (o[db][4 * g + 3] * inv);
;                 o[db][4 * g] = x0; o[db][4 * g + 1] = x1; o[db][4 * g + 2] = x2; o[db][4 * g + 3] = x3; ss += (x0 * x0 + x1 * x1) + (x2 * x2 + x3 * x3); }
	v_lshlrev_b32_e32 v134, 16, v98
	v_pk_fma_f32 v[86:87], v[86:87], v[86:87], v[88:89]
	v_and_b32_e32 v135, 0xffff0000, v98
	v_lshlrev_b32_e32 v126, 16, v99
	v_and_b32_e32 v127, 0xffff0000, v99
	v_pk_add_f32 v[98:99], v[86:87], v[86:87] op_sel:[0,1] op_sel_hi:[1,0]
	v_pk_mul_f32 v[86:87], v[34:35], v[66:67] op_sel_hi:[1,0]
	v_lshlrev_b32_e32 v120, 16, v100
	v_pk_fma_f32 v[86:87], v[86:87], v[70:71], v[136:137] op_sel_hi:[1,0,1] neg_lo:[1,0,0] neg_hi:[1,0,0]
	v_and_b32_e32 v121, 0xffff0000, v100
	v_mul_f32_e32 v88, v87, v87
	v_lshlrev_b32_e32 v130, 16, v101
	v_and_b32_e32 v131, 0xffff0000, v101
	v_pk_fma_f32 v[100:101], v[86:87], v[86:87], v[88:89] op_sel_hi:[1,1,0]
	v_pk_mul_f32 v[88:89], v[32:33], v[66:67] op_sel_hi:[1,0]
	v_pk_mul_f32 v[94:95], v[36:37], v[66:67] op_sel_hi:[1,0]
	v_pk_fma_f32 v[92:93], v[88:89], v[70:71], v[116:117] op_sel_hi:[1,0,1] neg_lo:[1,0,0] neg_hi:[1,0,0]
	v_pk_fma_f32 v[94:95], v[94:95], v[70:71], v[138:139] op_sel_hi:[1,0,1] neg_lo:[1,0,0] neg_hi:[1,0,0]
	v_mul_f32_e32 v88, v93, v93
	v_pk_fma_f32 v[102:103], v[92:93], v[92:93], v[88:89] op_sel_hi:[1,1,0]
	v_pk_mul_f32 v[88:89], v[38:39], v[66:67] op_sel_hi:[1,0]
	v_pk_mul_f32 v[106:107], v[94:95], v[94:95]
	v_pk_fma_f32 v[88:89], v[88:89], v[70:71], v[140:141] op_sel_hi:[1,0,1] neg_lo:[1,0,0] neg_hi:[1,0,0]
	v_mov_b32_e32 v97, v106
	v_pk_mul_f32 v[104:105], v[88:89], v[88:89]
	v_mov_b32_e32 v99, v107
	v_mov_b32_e32 v103, v104
	v_mov_b32_e32 v101, v105
	v_pk_add_f32 v[100:101], v[102:103], v[100:101]
	v_pk_add_f32 v[96:97], v[96:97], v[98:99]
	v_pk_mul_f32 v[98:99], v[40:41], v[66:67] op_sel_hi:[1,0]
	v_pk_add_f32 v[96:97], v[96:97], v[100:101]
	v_pk_fma_f32 v[102:103], v[98:99], v[70:71], v[142:143] op_sel_hi:[1,0,1] neg_lo:[1,0,0] neg_hi:[1,0,0]
	v_pk_add_f32 v[108:109], v[96:97], v[96:97] op_sel:[0,1] op_sel_hi:[1,0]
	v_pk_mul_f32 v[96:97], v[42:43], v[66:67] op_sel_hi:[1,0]
	v_mov_b32_e32 v100, v103
	v_pk_fma_f32 v[96:97], v[96:97], v[70:71], v[144:145] op_sel_hi:[1,0,1] neg_lo:[1,0,0] neg_hi:[1,0,0]
	v_mov_b32_e32 v98, v102
	v_mov_b32_e32 v101, v97
	v_mov_b32_e32 v99, v96
	v_pk_mul_f32 v[100:101], v[100:101], v[100:101]
	v_pk_mul_f32 v[104:105], v[16:17], v[66:67] op_sel_hi:[1,0]
	v_pk_fma_f32 v[98:99], v[98:99], v[98:99], v[100:101]
	v_pk_fma_f32 v[104:105], v[104:105], v[70:71], v[150:151] op_sel_hi:[1,0,1] neg_lo:[1,0,0] neg_hi:[1,0,0]
	v_pk_add_f32 v[110:111], v[98:99], v[98:99] op_sel:[0,1] op_sel_hi:[1,0]
	v_pk_mul_f32 v[98:99], v[46:47], v[66:67] op_sel_hi:[1,0]
	v_pk_mul_f32 v[140:141], v[104:105], v[104:105]
	v_pk_fma_f32 v[98:99], v[98:99], v[70:71], v[148:149] op_sel_hi:[1,0,1] neg_lo:[1,0,0] neg_hi:[1,0,0]
	v_mov_b32_e32 v109, v140
	v_mul_f32_e32 v100, v99, v99
	v_pk_fma_f32 v[116:117], v[98:99], v[98:99], v[100:101] op_sel_hi:[1,1,0]
	v_pk_mul_f32 v[100:101], v[44:45], v[66:67] op_sel_hi:[1,0]
	v_mov_b32_e32 v111, v141
	v_pk_fma_f32 v[106:107], v[100:101], v[70:71], v[146:147] op_sel_hi:[1,0,1] neg_lo:[1,0,0] neg_hi:[1,0,0]
	v_pk_add_f32 v[108:109], v[108:109], v[110:111]
	v_mul_f32_e32 v100, v107, v107
	v_pk_fma_f32 v[136:137], v[106:107], v[106:107], v[100:101] op_sel_hi:[1,1,0]
	v_pk_mul_f32 v[100:101], v[18:19], v[66:67] op_sel_hi:[1,0]
	v_pk_mul_f32 v[110:111], v[20:21], v[66:67] op_sel_hi:[1,0]
	v_pk_fma_f32 v[100:101], v[100:101], v[70:71], v[152:153] op_sel_hi:[1,0,1] neg_lo:[1,0,0] neg_hi:[1,0,0]
	v_pk_mul_f32 v[146:147], v[28:29], v[66:67] op_sel_hi:[1,0]
	v_pk_mul_f32 v[138:139], v[100:101], v[100:101]
	v_pk_mul_f32 v[142:143], v[24:25], v[66:67] op_sel_hi:[1,0]
	v_mov_b32_e32 v137, v138
	v_mov_b32_e32 v117, v139
	v_pk_add_f32 v[116:117], v[136:137], v[116:117]
	v_pk_fma_f32 v[122:123], v[146:147], v[70:71], v[122:123] op_sel_hi:[1,0,1] neg_lo:[1,0,0] neg_hi:[1,0,0]
	v_pk_add_f32 v[108:109], v[108:109], v[116:117]
	v_pk_fma_f32 v[116:117], v[110:111], v[70:71], v[154:155] op_sel_hi:[1,0,1] neg_lo:[1,0,0] neg_hi:[1,0,0]
	v_pk_add_f32 v[136:137], v[108:109], v[108:109] op_sel:[0,1] op_sel_hi:[1,0]
	v_pk_mul_f32 v[108:109], v[22:23], v[66:67] op_sel_hi:[1,0]
	v_mov_b32_e32 v138, v117
	v_pk_fma_f32 v[108:109], v[108:109], v[70:71], v[156:157] op_sel_hi:[1,0,1] neg_lo:[1,0,0] neg_hi:[1,0,0]
	v_mov_b32_e32 v110, v116
	v_mov_b32_e32 v139, v109
	v_mov_b32_e32 v111, v108
	v_pk_mul_f32 v[138:139], v[138:139], v[138:139]
	v_pk_fma_f32 v[118:119], v[142:143], v[70:71], v[118:119] op_sel_hi:[1,0,1] neg_lo:[1,0,0] neg_hi:[1,0,0]
	v_pk_fma_f32 v[110:111], v[110:111], v[110:111], v[138:139]
	v_pk_mul_f32 v[144:145], v[30:31], v[66:67] op_sel_hi:[1,0]
	v_pk_add_f32 v[138:139], v[110:111], v[110:111] op_sel:[0,1] op_sel_hi:[1,0]
	v_pk_mul_f32 v[110:111], v[26:27], v[66:67] op_sel_hi:[1,0]
	v_pk_mul_f32 v[146:147], v[122:123], v[122:123]
	v_pk_fma_f32 v[110:111], v[110:111], v[70:71], v[158:159] op_sel_hi:[1,0,1] neg_lo:[1,0,0] neg_hi:[1,0,0]
	v_mul_f32_e32 v142, v119, v119
	v_mul_f32_e32 v140, v111, v111
	v_pk_fma_f32 v[112:113], v[144:145], v[70:71], v[112:113] op_sel_hi:[1,0,1] neg_lo:[1,0,0] neg_hi:[1,0,0]
	v_mov_b32_e32 v137, v146
	v_mov_b32_e32 v139, v147
	v_pk_fma_f32 v[140:141], v[110:111], v[110:111], v[140:141] op_sel_hi:[1,1,0]
	v_pk_fma_f32 v[142:143], v[118:119], v[118:119], v[142:143] op_sel_hi:[1,1,0]
	v_pk_mul_f32 v[144:145], v[112:113], v[112:113]
	v_pk_add_f32 v[136:137], v[136:137], v[138:139]
	v_pk_mul_f32 v[138:139], v[2:3], v[66:67] op_sel_hi:[1,0]
	v_mov_b32_e32 v143, v144
	v_mov_b32_e32 v141, v145
	v_pk_fma_f32 v[124:125], v[138:139], v[70:71], v[124:125] op_sel_hi:[1,0,1] neg_lo:[1,0,0] neg_hi:[1,0,0]
	v_pk_mul_f32 v[138:139], v[0:1], v[66:67] op_sel_hi:[1,0]
	v_pk_add_f32 v[140:141], v[142:143], v[140:141]
; __device__ __forceinline__ unsigned cvtpk(float lo, float hi) { f32x2_t v = {lo, hi}; bf16x2_t b = __builtin_convertvector(v, bf16x2_t); return __builtin_bit_cast(unsigned, b); }
; __device__ __forceinline__ float xhalf_sum(float m) { unsigned a = __builtin_bit_cast(unsigned, m), b = a; xswap(a, b); return __builtin_bit_cast(float, a) + __builtin_bit_cast(float, b); }
; __device__ __forceinline__ void attn_unit_a(FLAS unsigned char* lds, const Unit u) {
;     ...
;                 const float x0 = a0 - lam * (o[db][4 * g] * inv), x1 = a1 - lam * (o[db][4 * g + 1] * inv), x2 = a2 - lam * (o[db][4 * g + 2] * inv), x3 = a3 - lam * (o[db][4 * g + 3] * inv);
;                 o[db][4 * g] = x0; o[db][4 * g + 1] = x1; o[db][4 * g + 2] = x2; o[db][4 * g + 3] = x3; ss += (x0 * x0 + x1 * x1) + (x2 * x2 + x3 * x3); }
;         const float rr = 1.0f / sqrtf(xhalf_sum(ss) * (1.f / 128.f) + 1e-6f) * gsc;
; #pragma unroll
;         for (int db = 0; db < NDB; ++db)
; #pragma unroll
;             for (int g = 0; g < 4; ++g) { const float* gp = u.sgain + db * 32 + 8 * g + 4 * hi; u32x2 w;
;                 w.x = cvtpk(o[db][4 * g] * rr * gp[0], o[db][4 * g + 1] * rr * gp[1]); w.y = cvtpk(o[db][4 * g + 2] * rr * gp[2], o[db][4 * g + 3] * rr * gp[3]);
;                 *(u32x2*)(op + db * 32 + 8 * g) = w; }
	v_pk_fma_f32 v[132:133], v[138:139], v[70:71], v[132:133] op_sel_hi:[1,0,1] neg_lo:[1,0,0] neg_hi:[1,0,0]
	v_pk_mul_f32 v[144:145], v[10:11], v[66:67] op_sel_hi:[1,0]
	v_pk_mul_f32 v[146:147], v[8:9], v[66:67] op_sel_hi:[1,0]
	v_pk_add_f32 v[136:137], v[136:137], v[140:141]
	v_mov_b32_e32 v140, v133
	v_mov_b32_e32 v141, v125
	v_pk_fma_f32 v[130:131], v[144:145], v[70:71], v[130:131] op_sel_hi:[1,0,1] neg_lo:[1,0,0] neg_hi:[1,0,0]
	v_pk_fma_f32 v[120:121], v[146:147], v[70:71], v[120:121] op_sel_hi:[1,0,1] neg_lo:[1,0,0] neg_hi:[1,0,0]
	v_mov_b32_e32 v138, v132
	v_mov_b32_e32 v139, v124
	v_pk_mul_f32 v[140:141], v[140:141], v[140:141]
	v_mul_f32_e32 v144, v131, v131
	v_mul_f32_e32 v146, v121, v121
	v_pk_mul_f32 v[128:129], v[68:69], v[68:69]
	v_pk_fma_f32 v[138:139], v[138:139], v[138:139], v[140:141]
	v_pk_mul_f32 v[140:141], v[6:7], v[66:67] op_sel_hi:[1,0]
	v_pk_mul_f32 v[142:143], v[4:5], v[66:67] op_sel_hi:[1,0]
	v_pk_fma_f32 v[144:145], v[130:131], v[130:131], v[144:145] op_sel_hi:[1,1,0]
	v_pk_fma_f32 v[146:147], v[120:121], v[120:121], v[146:147] op_sel_hi:[1,1,0]
	v_pk_fma_f32 v[126:127], v[140:141], v[70:71], v[126:127] op_sel_hi:[1,0,1] neg_lo:[1,0,0] neg_hi:[1,0,0]
	v_pk_fma_f32 v[134:135], v[142:143], v[70:71], v[134:135] op_sel_hi:[1,0,1] neg_lo:[1,0,0] neg_hi:[1,0,0]
	v_mov_b32_e32 v147, v128
	v_mov_b32_e32 v145, v129
	v_mul_f32_e32 v140, v127, v127
	v_mul_f32_e32 v142, v135, v135
	v_pk_add_f32 v[128:129], v[146:147], v[144:145]
	v_pk_mul_f32 v[144:145], v[12:13], v[66:67] op_sel_hi:[1,0]
	v_pk_add_f32 v[136:137], v[136:137], v[136:137] op_sel:[0,1] op_sel_hi:[1,0]
	v_pk_add_f32 v[138:139], v[138:139], v[138:139] op_sel:[0,1] op_sel_hi:[1,0]
	v_pk_fma_f32 v[140:141], v[126:127], v[126:127], v[140:141] op_sel_hi:[1,1,0]
	v_pk_fma_f32 v[142:143], v[134:135], v[134:135], v[142:143] op_sel_hi:[1,1,0]
	v_pk_fma_f32 v[70:71], v[144:145], v[70:71], v[114:115] op_sel_hi:[1,0,1] neg_lo:[1,0,0] neg_hi:[1,0,0]
	v_pk_add_f32 v[114:115], v[136:137], v[138:139]
	v_pk_mul_f32 v[136:137], v[70:71], v[70:71]
	v_pk_add_f32 v[138:139], v[142:143], v[140:141]
	v_mov_b32_e32 v115, v136
	v_mov_b32_e32 v139, v137
	v_pk_add_f32 v[114:115], v[114:115], v[138:139]
	s_nop 0
	v_pk_add_f32 v[114:115], v[114:115], v[128:129]
	s_nop 0
	v_pk_add_f32 v[114:115], v[114:115], v[114:115] op_sel:[0,1] op_sel_hi:[1,0]
	s_nop 0
	v_mov_b32_e32 v115, v114
	s_nop 1
	v_permlane32_swap_b32 v115, v114
	s_nop 1
	global_load_dwordx4 v[136:139], v67, s[8:9]
	v_add_f32_e32 v114, v115, v114
	v_fmamk_f32 v114, v114, 0x3c000000, v240
	v_mul_f32_e32 v115, 0x4f800000, v114
	v_cmp_gt_f32_e32 vcc, s35, v114
	s_nop 1
	v_cndmask_b32_e32 v114, v114, v115, vcc
	v_sqrt_f32_e32 v115, v114
	s_nop 0
	v_add_u32_e32 v128, -1, v115
	v_fma_f32 v129, -v128, v115, v114
	v_cmp_ge_f32_e64 s[4:5], 0, v129
	v_add_u32_e32 v129, 1, v115
	s_nop 0
	v_cndmask_b32_e64 v128, v115, v128, s[4:5]
	v_fma_f32 v115, -v129, v115, v114
	v_cmp_lt_f32_e64 s[4:5], 0, v115
	s_nop 1
	v_cndmask_b32_e64 v115, v128, v129, s[4:5]
	v_mul_f32_e32 v128, 0x37800000, v115
	v_cndmask_b32_e32 v115, v115, v128, vcc
	v_cmp_class_f32_e32 vcc, v114, v244
	s_mov_b64 s[4:5], 0
	s_nop 0
	v_cndmask_b32_e32 v114, v115, v114, vcc
	v_div_scale_f32 v115, s[0:1], v114, v114, 1.0
	v_rcp_f32_e32 v128, v115
	s_nop 0
	v_fma_f32 v129, -v115, v128, 1.0
	v_fmac_f32_e32 v128, v129, v128
	v_div_scale_f32 v129, vcc, 1.0, v114, 1.0
	v_mul_f32_e32 v140, v129, v128
	v_fma_f32 v141, -v115, v140, v129
	v_fmac_f32_e32 v140, v141, v128
	v_fma_f32 v115, -v115, v140, v129
	v_div_fmas_f32 v115, v115, v128, v140
	v_div_fixup_f32 v114, v115, v114, 1.0
	v_mul_f32_e32 v114, v237, v114
	v_pk_mul_f32 v[78:79], v[78:79], v[114:115] op_sel_hi:[1,0]
	v_pk_mul_f32 v[72:73], v[72:73], v[114:115] op_sel_hi:[1,0]
	v_pk_mul_f32 v[74:75], v[74:75], v[114:115] op_sel_hi:[1,0]
	v_pk_mul_f32 v[76:77], v[76:77], v[114:115] op_sel_hi:[1,0]
	v_pk_mul_f32 v[70:71], v[70:71], v[114:115] op_sel_hi:[1,0]
	v_pk_mul_f32 v[68:69], v[68:69], v[114:115] op_sel_hi:[1,0]
	s_waitcnt vmcnt(0)
	v_pk_mul_f32 v[78:79], v[136:137], v[78:79]
	v_pk_mul_f32 v[72:73], v[138:139], v[72:73]
	v_cvt_pk_bf16_f32 v78, v78, v79
	v_cvt_pk_bf16_f32 v79, v72, v73
	global_store_dwordx2 v[64:65], v[78:79], off
	global_load_dwordx4 v[136:139], v67, s[8:9] offset:32
	v_pk_mul_f32 v[72:73], v[80:81], v[114:115] op_sel_hi:[1,0]
	v_pk_mul_f32 v[78:79], v[82:83], v[114:115] op_sel_hi:[1,0]
	s_waitcnt vmcnt(0)
	v_pk_mul_f32 v[72:73], v[136:137], v[72:73]
	v_pk_mul_f32 v[74:75], v[138:139], v[74:75]
	v_cvt_pk_bf16_f32 v72, v72, v73
	v_cvt_pk_bf16_f32 v73, v74, v75
	global_store_dwordx2 v[64:65], v[72:73], off offset:16
	global_load_dwordx4 v[72:75], v67, s[8:9] offset:64
	s_waitcnt vmcnt(0)
	v_pk_mul_f32 v[72:73], v[78:79], v[72:73]
	v_pk_mul_f32 v[74:75], v[76:77], v[74:75]
	v_cvt_pk_bf16_f32 v72, v72, v73
	v_cvt_pk_bf16_f32 v73, v74, v75
	global_store_dwordx2 v[64:65], v[72:73], off offset:32
	global_load_dwordx4 v[72:75], v67, s[8:9] offset:96
	v_pk_mul_f32 v[76:77], v[90:91], v[114:115] op_sel_hi:[1,0]
	v_pk_mul_f32 v[78:79], v[84:85], v[114:115] op_sel_hi:[1,0]
	s_waitcnt vmcnt(0)
; __device__ __forceinline__ unsigned cvtpk(float lo, float hi) { f32x2_t v = {lo, hi}; bf16x2_t b = __builtin_convertvector(v, bf16x2_t); return __builtin_bit_cast(unsigned, b); }
; __device__ __forceinline__ void attn_unit_a(FLAS unsigned char* lds, const Unit u) {
;     ...
; #pragma unroll
;         for (int db = 0; db < NDB; ++db)
; #pragma unroll
;             for (int g = 0; g < 4; ++g) { const float* gp = u.sgain + db * 32 + 8 * g + 4 * hi; u32x2 w;
;                 w.x = cvtpk(o[db][4 * g] * rr * gp[0], o[db][4 * g + 1] * rr * gp[1]); w.y = cvtpk(o[db][4 * g + 2] * rr * gp[2], o[db][4 * g + 3] * rr * gp[3]);
;                 *(u32x2*)(op + db * 32 + 8 * g) = w; }
	v_pk_mul_f32 v[72:73], v[76:77], v[72:73]
	v_pk_mul_f32 v[74:75], v[78:79], v[74:75]
	v_cvt_pk_bf16_f32 v72, v72, v73
	v_cvt_pk_bf16_f32 v73, v74, v75
	global_store_dwordx2 v[64:65], v[72:73], off offset:48
	global_load_dwordx4 v[72:75], v67, s[8:9] offset:128
	v_pk_mul_f32 v[76:77], v[92:93], v[114:115] op_sel_hi:[1,0]
	v_pk_mul_f32 v[78:79], v[86:87], v[114:115] op_sel_hi:[1,0]
	s_waitcnt vmcnt(0)
	v_pk_mul_f32 v[72:73], v[76:77], v[72:73]
	v_pk_mul_f32 v[74:75], v[78:79], v[74:75]
	v_cvt_pk_bf16_f32 v72, v72, v73
	v_cvt_pk_bf16_f32 v73, v74, v75
	global_store_dwordx2 v[64:65], v[72:73], off offset:64
	global_load_dwordx4 v[72:75], v67, s[8:9] offset:160
	v_pk_mul_f32 v[76:77], v[94:95], v[114:115] op_sel_hi:[1,0]
	v_pk_mul_f32 v[78:79], v[88:89], v[114:115] op_sel_hi:[1,0]
	s_waitcnt vmcnt(0)
	v_pk_mul_f32 v[72:73], v[76:77], v[72:73]
	v_pk_mul_f32 v[74:75], v[78:79], v[74:75]
	v_cvt_pk_bf16_f32 v72, v72, v73
	v_cvt_pk_bf16_f32 v73, v74, v75
	global_store_dwordx2 v[64:65], v[72:73], off offset:80
	global_load_dwordx4 v[72:75], v67, s[8:9] offset:192
	v_pk_mul_f32 v[76:77], v[102:103], v[114:115] op_sel_hi:[1,0]
	v_pk_mul_f32 v[78:79], v[96:97], v[114:115] op_sel_hi:[1,0]
	s_waitcnt vmcnt(0)
	v_pk_mul_f32 v[72:73], v[76:77], v[72:73]
	v_pk_mul_f32 v[74:75], v[78:79], v[74:75]
	v_cvt_pk_bf16_f32 v72, v72, v73
	v_cvt_pk_bf16_f32 v73, v74, v75
	global_store_dwordx2 v[64:65], v[72:73], off offset:96
	global_load_dwordx4 v[72:75], v67, s[8:9] offset:224
	v_pk_mul_f32 v[76:77], v[106:107], v[114:115] op_sel_hi:[1,0]
	v_pk_mul_f32 v[78:79], v[98:99], v[114:115] op_sel_hi:[1,0]
	s_waitcnt vmcnt(0)
	v_pk_mul_f32 v[72:73], v[76:77], v[72:73]
	v_pk_mul_f32 v[74:75], v[78:79], v[74:75]
	v_cvt_pk_bf16_f32 v72, v72, v73
	v_cvt_pk_bf16_f32 v73, v74, v75
	global_store_dwordx2 v[64:65], v[72:73], off offset:112
	global_load_dwordx4 v[72:75], v67, s[8:9] offset:256
	v_pk_mul_f32 v[76:77], v[104:105], v[114:115] op_sel_hi:[1,0]
	v_pk_mul_f32 v[78:79], v[100:101], v[114:115] op_sel_hi:[1,0]
	s_waitcnt vmcnt(0)
	v_pk_mul_f32 v[72:73], v[76:77], v[72:73]
	v_pk_mul_f32 v[74:75], v[78:79], v[74:75]
	v_cvt_pk_bf16_f32 v72, v72, v73
	v_cvt_pk_bf16_f32 v73, v74, v75
	global_store_dwordx2 v[64:65], v[72:73], off offset:128
	global_load_dwordx4 v[72:75], v67, s[8:9] offset:288
	v_pk_mul_f32 v[76:77], v[116:117], v[114:115] op_sel_hi:[1,0]
	v_pk_mul_f32 v[78:79], v[108:109], v[114:115] op_sel_hi:[1,0]
	s_waitcnt vmcnt(0)
	v_pk_mul_f32 v[72:73], v[76:77], v[72:73]
	v_pk_mul_f32 v[74:75], v[78:79], v[74:75]
	v_cvt_pk_bf16_f32 v72, v72, v73
	v_cvt_pk_bf16_f32 v73, v74, v75
	global_store_dwordx2 v[64:65], v[72:73], off offset:144
	global_load_dwordx4 v[72:75], v67, s[8:9] offset:320
	v_pk_mul_f32 v[76:77], v[118:119], v[114:115] op_sel_hi:[1,0]
	v_pk_mul_f32 v[78:79], v[110:111], v[114:115] op_sel_hi:[1,0]
	s_waitcnt vmcnt(0)
	v_pk_mul_f32 v[72:73], v[76:77], v[72:73]
	v_pk_mul_f32 v[74:75], v[78:79], v[74:75]
	v_cvt_pk_bf16_f32 v72, v72, v73
	v_cvt_pk_bf16_f32 v73, v74, v75
	global_store_dwordx2 v[64:65], v[72:73], off offset:160
	global_load_dwordx4 v[72:75], v67, s[8:9] offset:352
	v_pk_mul_f32 v[76:77], v[122:123], v[114:115] op_sel_hi:[1,0]
	v_pk_mul_f32 v[78:79], v[112:113], v[114:115] op_sel_hi:[1,0]
	s_waitcnt vmcnt(0)
	v_pk_mul_f32 v[72:73], v[76:77], v[72:73]
	v_pk_mul_f32 v[74:75], v[78:79], v[74:75]
	v_cvt_pk_bf16_f32 v72, v72, v73
	v_cvt_pk_bf16_f32 v73, v74, v75
	global_store_dwordx2 v[64:65], v[72:73], off offset:176
	global_load_dwordx4 v[72:75], v67, s[8:9] offset:384
	v_pk_mul_f32 v[76:77], v[132:133], v[114:115] op_sel_hi:[1,0]
	v_pk_mul_f32 v[78:79], v[124:125], v[114:115] op_sel_hi:[1,0]
	s_waitcnt vmcnt(0)
	v_pk_mul_f32 v[72:73], v[76:77], v[72:73]
	v_pk_mul_f32 v[74:75], v[78:79], v[74:75]
	v_cvt_pk_bf16_f32 v72, v72, v73
	v_cvt_pk_bf16_f32 v73, v74, v75
	global_store_dwordx2 v[64:65], v[72:73], off offset:192
	global_load_dwordx4 v[72:75], v67, s[8:9] offset:416
	v_pk_mul_f32 v[76:77], v[134:135], v[114:115] op_sel_hi:[1,0]
	v_pk_mul_f32 v[78:79], v[126:127], v[114:115] op_sel_hi:[1,0]
	s_waitcnt vmcnt(0)
	v_pk_mul_f32 v[72:73], v[76:77], v[72:73]
	v_pk_mul_f32 v[74:75], v[78:79], v[74:75]
	v_cvt_pk_bf16_f32 v72, v72, v73
	v_cvt_pk_bf16_f32 v73, v74, v75
	global_store_dwordx2 v[64:65], v[72:73], off offset:208
	global_load_dwordx4 v[72:75], v67, s[8:9] offset:448
	v_pk_mul_f32 v[76:77], v[120:121], v[114:115] op_sel_hi:[1,0]
	v_pk_mul_f32 v[78:79], v[130:131], v[114:115] op_sel_hi:[1,0]
	s_waitcnt vmcnt(0)
	v_pk_mul_f32 v[72:73], v[76:77], v[72:73]
	v_pk_mul_f32 v[74:75], v[78:79], v[74:75]
	v_cvt_pk_bf16_f32 v72, v72, v73
	v_cvt_pk_bf16_f32 v73, v74, v75
	global_store_dwordx2 v[64:65], v[72:73], off offset:224
	global_load_dwordx4 v[72:75], v67, s[8:9] offset:480
	s_waitcnt vmcnt(0)
	v_pk_mul_f32 v[72:73], v[70:71], v[72:73]
	v_pk_mul_f32 v[70:71], v[68:69], v[74:75]
	v_cvt_pk_bf16_f32 v68, v72, v73

; #define LAS __attribute__((address_space(3)))
; __global__ void __launch_bounds__(NWAVES * 64, 2) fwd_megakernel(Params P) {
;     extern __shared__ __attribute__((aligned(16))) unsigned char lds_raw[];
;     cg::grid_group grid = cg::this_grid();
;     LAS unsigned char* lds = (LAS unsigned char*)lds_raw;
;     const int tid = threadIdx.x, lane = tid & 63, wave = __builtin_amdgcn_readfirstlane(tid >> 6);
	.amdhsa_kernel _Z14fwd_megakernel6Params
		.amdhsa_group_segment_fixed_size 0
		.amdhsa_private_segment_fixed_size 0
		.amdhsa_kernarg_size 456
		.amdhsa_user_sgpr_count 2
		.amdhsa_user_sgpr_dispatch_ptr 0
		.amdhsa_user_sgpr_queue_ptr 0
		.amdhsa_user_sgpr_kernarg_segment_ptr 1
		.amdhsa_user_sgpr_dispatch_id 0
		.amdhsa_user_sgpr_kernarg_preload_length 0
		.amdhsa_user_sgpr_kernarg_preload_offset 0
		.amdhsa_user_sgpr_private_segment_size 0
		.amdhsa_uses_dynamic_stack 0
		.amdhsa_enable_private_segment 0
		.amdhsa_system_sgpr_workgroup_id_x 1
		.amdhsa_system_sgpr_workgroup_id_y 0
		.amdhsa_system_sgpr_workgroup_id_z 0
		.amdhsa_system_sgpr_workgroup_info 0
		.amdhsa_system_vgpr_workitem_id 2
		.amdhsa_next_free_vgpr 256
		.amdhsa_next_free_sgpr 102
		.amdhsa_accum_offset 256
		.amdhsa_reserve_vcc 1
		.amdhsa_float_round_mode_32 0
		.amdhsa_float_round_mode_16_64 0
		.amdhsa_float_denorm_mode_32 3
		.amdhsa_float_denorm_mode_16_64 3
		.amdhsa_dx10_clamp 1
		.amdhsa_ieee_mode 1
		.amdhsa_fp16_overflow 0
		.amdhsa_tg_split 0
		.amdhsa_exception_fp_ieee_invalid_op 0
		.amdhsa_exception_fp_denorm_src 0
		.amdhsa_exception_fp_ieee_div_zero 0
		.amdhsa_exception_fp_ieee_overflow 0
		.amdhsa_exception_fp_ieee_underflow 0
		.amdhsa_exception_fp_ieee_inexact 0
		.amdhsa_exception_int_div_zero 0
	.end_amdhsa_kernel

; #define LAS __attribute__((address_space(3)))
; __global__ void __launch_bounds__(NWAVES * 64, 2) fwd_megakernel(Params P) {
;     extern __shared__ __attribute__((aligned(16))) unsigned char lds_raw[];
;     cg::grid_group grid = cg::this_grid();
;     LAS unsigned char* lds = (LAS unsigned char*)lds_raw;
;     const int tid = threadIdx.x, lane = tid & 63, wave = __builtin_amdgcn_readfirstlane(tid >> 6);
amdhsa.kernels:
  - .agpr_count:     0
    .args:
      - .offset:         0
        .size:           200
        .value_kind:     by_value
      - .offset:         200
        .size:           4
        .value_kind:     hidden_block_count_x
      - .offset:         204
        .size:           4
        .value_kind:     hidden_block_count_y
      - .offset:         208
        .size:           4
        .value_kind:     hidden_block_count_z
      - .offset:         212
        .size:           2
        .value_kind:     hidden_group_size_x
      - .offset:         214
        .size:           2
        .value_kind:     hidden_group_size_y
      - .offset:         216
        .size:           2
        .value_kind:     hidden_group_size_z
      - .offset:         218
        .size:           2
        .value_kind:     hidden_remainder_x
      - .offset:         220
        .size:           2
        .value_kind:     hidden_remainder_y
      - .offset:         222
        .size:           2
        .value_kind:     hidden_remainder_z
      - .offset:         240
        .size:           8
        .value_kind:     hidden_global_offset_x
      - .offset:         248
        .size:           8
        .value_kind:     hidden_global_offset_y
      - .offset:         256
        .size:           8
        .value_kind:     hidden_global_offset_z
      - .offset:         264
        .size:           2
        .value_kind:     hidden_grid_dims
      - .offset:         288
        .size:           8
        .value_kind:     hidden_multigrid_sync_arg
      - .offset:         320
        .size:           4
        .value_kind:     hidden_dynamic_lds_size
    .group_segment_fixed_size: 0
    .kernarg_segment_align: 8
    .kernarg_segment_size: 456
    .language:       OpenCL C
    .language_version:
      - 2
      - 0
    .max_flat_workgroup_size: 512
    .name:           _Z14fwd_megakernel6Params
    .private_segment_fixed_size: 0
    .sgpr_count:     108
    .sgpr_spill_count: 228
    .symbol:         _Z14fwd_megakernel6Params.kd
    .uniform_work_group_size: 1
    .uses_dynamic_stack: false
    .vgpr_count:     256
    .vgpr_spill_count: 0
    .wavefront_size: 64
